# v74 plus hand-written MLP1A/B and GIN tiles: epilogue stores widened to 16 bytes per lane (v_permlane16_swap pairs -> global_store_dwordx4)
# speedup vs baseline: 1.0231x; 1.0204x over previous
.Lt_mlp1b:
	v_add_u32_e32 v169, s32, v164
	v_mfma_f32_16x16x32_f16 v[4:7], v[132:135], v[184:187], v[4:7]
	ds_read_b128 v[238:241], v169 offset:4112
	v_mfma_f32_16x16x32_f16 v[8:11], v[136:139], v[184:187], v[8:11]
	ds_read_b128 v[242:245], v169 offset:5136
	v_mfma_f32_16x16x32_f16 v[12:15], v[140:143], v[184:187], v[12:15]
	ds_read_b128 v[246:249], v169 offset:6160
	v_mfma_f32_16x16x32_f16 v[16:19], v[144:147], v[184:187], v[16:19]
	ds_read_b128 v[250:253], v169 offset:7184
	v_mfma_f32_16x16x32_f16 v[20:23], v[132:135], v[188:191], v[20:23]
	v_mfma_f32_16x16x32_f16 v[24:27], v[136:139], v[188:191], v[24:27]
	v_mfma_f32_16x16x32_f16 v[28:31], v[140:143], v[188:191], v[28:31]
	v_mfma_f32_16x16x32_f16 v[32:35], v[144:147], v[188:191], v[32:35]
	v_mfma_f32_16x16x32_f16 v[36:39], v[132:135], v[192:195], v[36:39]
	v_mfma_f32_16x16x32_f16 v[40:43], v[136:139], v[192:195], v[40:43]
	v_mfma_f32_16x16x32_f16 v[44:47], v[140:143], v[192:195], v[44:47]
	v_mfma_f32_16x16x32_f16 v[48:51], v[144:147], v[192:195], v[48:51]
	v_mfma_f32_16x16x32_f16 v[52:55], v[132:135], v[196:199], v[52:55]
	v_mfma_f32_16x16x32_f16 v[56:59], v[136:139], v[196:199], v[56:59]
	v_mfma_f32_16x16x32_f16 v[60:63], v[140:143], v[196:199], v[60:63]
	v_mfma_f32_16x16x32_f16 v[64:67], v[144:147], v[196:199], v[64:67]
	s_waitcnt vmcnt(8) lgkmcnt(0)
	s_barrier
	s_add_i32 s37, s32, 0x8000
	s_cmp_lg_u32 s32, 0x18000
	s_cselect_b32 s37, s37, 0
	v_add_u32_e32 v168, s37, v165
	v_add_u32_e32 v169, s37, v164
	s_add_u32 vcc_lo, s24, s32
	v_mfma_f32_16x16x32_f16 v[68:71], v[132:135], v[238:241], v[68:71]
	ds_read_b128 v[148:151], v168 offset:16
	ds_read_b128 v[184:187], v169 offset:16
	v_mfma_f32_16x16x32_f16 v[72:75], v[136:139], v[238:241], v[72:75]
	ds_read_b128 v[152:155], v168 offset:1040
	ds_read_b128 v[188:191], v169 offset:1040
	v_mfma_f32_16x16x32_f16 v[76:79], v[140:143], v[238:241], v[76:79]
	ds_read_b128 v[156:159], v168 offset:2064
	ds_read_b128 v[192:195], v169 offset:2064
	v_mfma_f32_16x16x32_f16 v[80:83], v[144:147], v[238:241], v[80:83]
	ds_read_b128 v[160:163], v168 offset:3088
	ds_read_b128 v[196:199], v169 offset:3088
	v_mfma_f32_16x16x32_f16 v[84:87], v[132:135], v[242:245], v[84:87]
	v_mfma_f32_16x16x32_f16 v[88:91], v[136:139], v[242:245], v[88:91]
	v_mfma_f32_16x16x32_f16 v[92:95], v[140:143], v[242:245], v[92:95]
	v_mfma_f32_16x16x32_f16 v[96:99], v[144:147], v[242:245], v[96:99]
	v_mfma_f32_16x16x32_f16 v[100:103], v[132:135], v[246:249], v[100:103]
	s_mov_b32 m0, vcc_lo
	s_nop 0
	global_load_lds_dwordx4 v170, s[30:31]
	v_mfma_f32_16x16x32_f16 v[104:107], v[136:139], v[246:249], v[104:107]
	s_add_u32 m0, vcc_lo, 0x400
	s_nop 0
	global_load_lds_dwordx4 v171, s[30:31]
	v_mfma_f32_16x16x32_f16 v[108:111], v[140:143], v[246:249], v[108:111]
	s_add_u32 m0, vcc_lo, 0x4000
	s_nop 0
	global_load_lds_dwordx4 v170, s[52:53]
	v_mfma_f32_16x16x32_f16 v[112:115], v[144:147], v[246:249], v[112:115]
	s_add_u32 m0, vcc_lo, 0x4400
	s_nop 0
	global_load_lds_dwordx4 v171, s[52:53]
	v_mfma_f32_16x16x32_f16 v[116:119], v[132:135], v[250:253], v[116:119]
	v_mfma_f32_16x16x32_f16 v[120:123], v[136:139], v[250:253], v[120:123]
	v_mfma_f32_16x16x32_f16 v[124:127], v[140:143], v[250:253], v[124:127]
	v_mfma_f32_16x16x32_f16 v[128:131], v[144:147], v[250:253], v[128:131]
	s_waitcnt lgkmcnt(0)
	s_mov_b32 s32, s37
	s_add_u32 s30, s30, 64
	s_addc_u32 s31, s31, 0
	s_add_u32 s52, s52, 64
	s_addc_u32 s53, s53, 0
	v_add_u32_e32 v169, s32, v164
	v_mfma_f32_16x16x32_f16 v[4:7], v[148:151], v[184:187], v[4:7]
	ds_read_b128 v[238:241], v169 offset:4112
	v_mfma_f32_16x16x32_f16 v[8:11], v[152:155], v[184:187], v[8:11]
	ds_read_b128 v[242:245], v169 offset:5136
	v_mfma_f32_16x16x32_f16 v[12:15], v[156:159], v[184:187], v[12:15]
	ds_read_b128 v[246:249], v169 offset:6160
	v_mfma_f32_16x16x32_f16 v[16:19], v[160:163], v[184:187], v[16:19]
	ds_read_b128 v[250:253], v169 offset:7184
	v_mfma_f32_16x16x32_f16 v[20:23], v[148:151], v[188:191], v[20:23]
	v_mfma_f32_16x16x32_f16 v[24:27], v[152:155], v[188:191], v[24:27]
	v_mfma_f32_16x16x32_f16 v[28:31], v[156:159], v[188:191], v[28:31]
	v_mfma_f32_16x16x32_f16 v[32:35], v[160:163], v[188:191], v[32:35]
	v_mfma_f32_16x16x32_f16 v[36:39], v[148:151], v[192:195], v[36:39]
	v_mfma_f32_16x16x32_f16 v[40:43], v[152:155], v[192:195], v[40:43]
	v_mfma_f32_16x16x32_f16 v[44:47], v[156:159], v[192:195], v[44:47]
	v_mfma_f32_16x16x32_f16 v[48:51], v[160:163], v[192:195], v[48:51]
	v_mfma_f32_16x16x32_f16 v[52:55], v[148:151], v[196:199], v[52:55]
	v_mfma_f32_16x16x32_f16 v[56:59], v[152:155], v[196:199], v[56:59]
	v_mfma_f32_16x16x32_f16 v[60:63], v[156:159], v[196:199], v[60:63]
	v_mfma_f32_16x16x32_f16 v[64:67], v[160:163], v[196:199], v[64:67]
	s_waitcnt vmcnt(8) lgkmcnt(0)
	s_barrier
	s_add_i32 s37, s32, 0x8000
	s_cmp_lg_u32 s32, 0x18000
	s_cselect_b32 s37, s37, 0
	v_add_u32_e32 v168, s37, v165
	v_add_u32_e32 v169, s37, v164
	s_add_u32 vcc_lo, s24, s32
	v_mfma_f32_16x16x32_f16 v[68:71], v[148:151], v[238:241], v[68:71]
	ds_read_b128 v[132:135], v168 offset:16
	ds_read_b128 v[184:187], v169 offset:16
	v_mfma_f32_16x16x32_f16 v[72:75], v[152:155], v[238:241], v[72:75]
	ds_read_b128 v[136:139], v168 offset:1040
	ds_read_b128 v[188:191], v169 offset:1040
	v_mfma_f32_16x16x32_f16 v[76:79], v[156:159], v[238:241], v[76:79]
	ds_read_b128 v[140:143], v168 offset:2064
	ds_read_b128 v[192:195], v169 offset:2064
	v_mfma_f32_16x16x32_f16 v[80:83], v[160:163], v[238:241], v[80:83]
	ds_read_b128 v[144:147], v168 offset:3088
	ds_read_b128 v[196:199], v169 offset:3088
	v_mfma_f32_16x16x32_f16 v[84:87], v[148:151], v[242:245], v[84:87]
	v_mfma_f32_16x16x32_f16 v[88:91], v[152:155], v[242:245], v[88:91]
	v_mfma_f32_16x16x32_f16 v[92:95], v[156:159], v[242:245], v[92:95]
	v_mfma_f32_16x16x32_f16 v[96:99], v[160:163], v[242:245], v[96:99]
	v_mfma_f32_16x16x32_f16 v[100:103], v[148:151], v[246:249], v[100:103]
	s_mov_b32 m0, vcc_lo
	s_nop 0
	global_load_lds_dwordx4 v170, s[30:31]
	v_mfma_f32_16x16x32_f16 v[104:107], v[152:155], v[246:249], v[104:107]
	s_add_u32 m0, vcc_lo, 0x400
	s_nop 0
	global_load_lds_dwordx4 v171, s[30:31]
	v_mfma_f32_16x16x32_f16 v[108:111], v[156:159], v[246:249], v[108:111]
	s_add_u32 m0, vcc_lo, 0x4000
	s_nop 0
	global_load_lds_dwordx4 v170, s[52:53]
	v_mfma_f32_16x16x32_f16 v[112:115], v[160:163], v[246:249], v[112:115]
	s_add_u32 m0, vcc_lo, 0x4400
	s_nop 0
	global_load_lds_dwordx4 v171, s[52:53]
	v_mfma_f32_16x16x32_f16 v[116:119], v[148:151], v[250:253], v[116:119]
	v_mfma_f32_16x16x32_f16 v[120:123], v[152:155], v[250:253], v[120:123]
	v_mfma_f32_16x16x32_f16 v[124:127], v[156:159], v[250:253], v[124:127]
	v_mfma_f32_16x16x32_f16 v[128:131], v[160:163], v[250:253], v[128:131]
	s_waitcnt lgkmcnt(0)
	s_mov_b32 s32, s37
	s_add_u32 s30, s30, 64
	s_addc_u32 s31, s31, 0
	s_add_u32 s52, s52, 64
	s_addc_u32 s53, s53, 0
	s_add_i32 s57, s57, 2
	s_cmp_lt_u32 s57, 28
	s_cbranch_scc1 .Lt_mlp1b
	v_add_u32_e32 v169, s32, v164
	v_mfma_f32_16x16x32_f16 v[4:7], v[132:135], v[184:187], v[4:7]
	ds_read_b128 v[238:241], v169 offset:4112
	v_mfma_f32_16x16x32_f16 v[8:11], v[136:139], v[184:187], v[8:11]
	ds_read_b128 v[242:245], v169 offset:5136
	v_mfma_f32_16x16x32_f16 v[12:15], v[140:143], v[184:187], v[12:15]
	ds_read_b128 v[246:249], v169 offset:6160
	v_mfma_f32_16x16x32_f16 v[16:19], v[144:147], v[184:187], v[16:19]
	ds_read_b128 v[250:253], v169 offset:7184
	v_mfma_f32_16x16x32_f16 v[20:23], v[132:135], v[188:191], v[20:23]
	v_mfma_f32_16x16x32_f16 v[24:27], v[136:139], v[188:191], v[24:27]
	v_mfma_f32_16x16x32_f16 v[28:31], v[140:143], v[188:191], v[28:31]
	v_mfma_f32_16x16x32_f16 v[32:35], v[144:147], v[188:191], v[32:35]
	v_mfma_f32_16x16x32_f16 v[36:39], v[132:135], v[192:195], v[36:39]
	v_mfma_f32_16x16x32_f16 v[40:43], v[136:139], v[192:195], v[40:43]
	v_mfma_f32_16x16x32_f16 v[44:47], v[140:143], v[192:195], v[44:47]
	v_mfma_f32_16x16x32_f16 v[48:51], v[144:147], v[192:195], v[48:51]
	v_mfma_f32_16x16x32_f16 v[52:55], v[132:135], v[196:199], v[52:55]
	v_mfma_f32_16x16x32_f16 v[56:59], v[136:139], v[196:199], v[56:59]
	v_mfma_f32_16x16x32_f16 v[60:63], v[140:143], v[196:199], v[60:63]
	v_mfma_f32_16x16x32_f16 v[64:67], v[144:147], v[196:199], v[64:67]
	s_waitcnt vmcnt(8) lgkmcnt(0)
	s_barrier
	s_add_i32 s37, s32, 0x8000
	s_cmp_lg_u32 s32, 0x18000
	s_cselect_b32 s37, s37, 0
	v_add_u32_e32 v168, s37, v165
	v_add_u32_e32 v169, s37, v164
	v_mfma_f32_16x16x32_f16 v[68:71], v[132:135], v[238:241], v[68:71]
	ds_read_b128 v[148:151], v168 offset:16
	ds_read_b128 v[184:187], v169 offset:16
	v_mfma_f32_16x16x32_f16 v[72:75], v[136:139], v[238:241], v[72:75]
	ds_read_b128 v[152:155], v168 offset:1040
	ds_read_b128 v[188:191], v169 offset:1040
	v_mfma_f32_16x16x32_f16 v[76:79], v[140:143], v[238:241], v[76:79]
	ds_read_b128 v[156:159], v168 offset:2064
	ds_read_b128 v[192:195], v169 offset:2064
	v_mfma_f32_16x16x32_f16 v[80:83], v[144:147], v[238:241], v[80:83]
	ds_read_b128 v[160:163], v168 offset:3088
	ds_read_b128 v[196:199], v169 offset:3088
	v_mfma_f32_16x16x32_f16 v[84:87], v[132:135], v[242:245], v[84:87]
	v_mfma_f32_16x16x32_f16 v[88:91], v[136:139], v[242:245], v[88:91]
	v_mfma_f32_16x16x32_f16 v[92:95], v[140:143], v[242:245], v[92:95]
	v_mfma_f32_16x16x32_f16 v[96:99], v[144:147], v[242:245], v[96:99]
	v_mfma_f32_16x16x32_f16 v[100:103], v[132:135], v[246:249], v[100:103]
	v_mfma_f32_16x16x32_f16 v[104:107], v[136:139], v[246:249], v[104:107]
	v_mfma_f32_16x16x32_f16 v[108:111], v[140:143], v[246:249], v[108:111]
	v_mfma_f32_16x16x32_f16 v[112:115], v[144:147], v[246:249], v[112:115]
	v_mfma_f32_16x16x32_f16 v[116:119], v[132:135], v[250:253], v[116:119]
	v_mfma_f32_16x16x32_f16 v[120:123], v[136:139], v[250:253], v[120:123]
	v_mfma_f32_16x16x32_f16 v[124:127], v[140:143], v[250:253], v[124:127]
	v_mfma_f32_16x16x32_f16 v[128:131], v[144:147], v[250:253], v[128:131]
	s_waitcnt lgkmcnt(0)
	s_mov_b32 s32, s37
	v_add_u32_e32 v169, s32, v164
	v_mfma_f32_16x16x32_f16 v[4:7], v[148:151], v[184:187], v[4:7]
	ds_read_b128 v[238:241], v169 offset:4112
	v_mfma_f32_16x16x32_f16 v[8:11], v[152:155], v[184:187], v[8:11]
	ds_read_b128 v[242:245], v169 offset:5136
	v_mfma_f32_16x16x32_f16 v[12:15], v[156:159], v[184:187], v[12:15]
	ds_read_b128 v[246:249], v169 offset:6160
	v_mfma_f32_16x16x32_f16 v[16:19], v[160:163], v[184:187], v[16:19]
	ds_read_b128 v[250:253], v169 offset:7184
	v_mfma_f32_16x16x32_f16 v[20:23], v[148:151], v[188:191], v[20:23]
	v_mfma_f32_16x16x32_f16 v[24:27], v[152:155], v[188:191], v[24:27]
	v_mfma_f32_16x16x32_f16 v[28:31], v[156:159], v[188:191], v[28:31]
	v_mfma_f32_16x16x32_f16 v[32:35], v[160:163], v[188:191], v[32:35]
	v_mfma_f32_16x16x32_f16 v[36:39], v[148:151], v[192:195], v[36:39]
	v_mfma_f32_16x16x32_f16 v[40:43], v[152:155], v[192:195], v[40:43]
	v_mfma_f32_16x16x32_f16 v[44:47], v[156:159], v[192:195], v[44:47]
	v_mfma_f32_16x16x32_f16 v[48:51], v[160:163], v[192:195], v[48:51]
	v_mfma_f32_16x16x32_f16 v[52:55], v[148:151], v[196:199], v[52:55]
	v_mfma_f32_16x16x32_f16 v[56:59], v[152:155], v[196:199], v[56:59]
	v_mfma_f32_16x16x32_f16 v[60:63], v[156:159], v[196:199], v[60:63]
	v_mfma_f32_16x16x32_f16 v[64:67], v[160:163], v[196:199], v[64:67]
	s_waitcnt vmcnt(4) lgkmcnt(0)
	s_barrier
	s_add_i32 s37, s32, 0x8000
	s_cmp_lg_u32 s32, 0x18000
	s_cselect_b32 s37, s37, 0
	v_add_u32_e32 v168, s37, v165
	v_add_u32_e32 v169, s37, v164
	v_mfma_f32_16x16x32_f16 v[68:71], v[148:151], v[238:241], v[68:71]
	ds_read_b128 v[132:135], v168 offset:16
	ds_read_b128 v[184:187], v169 offset:16
	v_mfma_f32_16x16x32_f16 v[72:75], v[152:155], v[238:241], v[72:75]
	ds_read_b128 v[136:139], v168 offset:1040
	ds_read_b128 v[188:191], v169 offset:1040
	v_mfma_f32_16x16x32_f16 v[76:79], v[156:159], v[238:241], v[76:79]
	ds_read_b128 v[140:143], v168 offset:2064
	ds_read_b128 v[192:195], v169 offset:2064
	v_mfma_f32_16x16x32_f16 v[80:83], v[160:163], v[238:241], v[80:83]
	ds_read_b128 v[144:147], v168 offset:3088
	ds_read_b128 v[196:199], v169 offset:3088
	v_mfma_f32_16x16x32_f16 v[84:87], v[148:151], v[242:245], v[84:87]
	v_mfma_f32_16x16x32_f16 v[88:91], v[152:155], v[242:245], v[88:91]
	v_mfma_f32_16x16x32_f16 v[92:95], v[156:159], v[242:245], v[92:95]
	v_mfma_f32_16x16x32_f16 v[96:99], v[160:163], v[242:245], v[96:99]
	v_mfma_f32_16x16x32_f16 v[100:103], v[148:151], v[246:249], v[100:103]
	v_mfma_f32_16x16x32_f16 v[104:107], v[152:155], v[246:249], v[104:107]
	v_mfma_f32_16x16x32_f16 v[108:111], v[156:159], v[246:249], v[108:111]
	v_mfma_f32_16x16x32_f16 v[112:115], v[160:163], v[246:249], v[112:115]
	v_mfma_f32_16x16x32_f16 v[116:119], v[148:151], v[250:253], v[116:119]
	v_mfma_f32_16x16x32_f16 v[120:123], v[152:155], v[250:253], v[120:123]
	v_mfma_f32_16x16x32_f16 v[124:127], v[156:159], v[250:253], v[124:127]
	v_mfma_f32_16x16x32_f16 v[128:131], v[160:163], v[250:253], v[128:131]
	s_waitcnt lgkmcnt(0)
	s_mov_b32 s32, s37
	v_add_u32_e32 v169, s32, v164
	v_mfma_f32_16x16x32_f16 v[4:7], v[132:135], v[184:187], v[4:7]
	ds_read_b128 v[238:241], v169 offset:4112
	v_mfma_f32_16x16x32_f16 v[8:11], v[136:139], v[184:187], v[8:11]
	ds_read_b128 v[242:245], v169 offset:5136
	v_mfma_f32_16x16x32_f16 v[12:15], v[140:143], v[184:187], v[12:15]
	ds_read_b128 v[246:249], v169 offset:6160
	v_mfma_f32_16x16x32_f16 v[16:19], v[144:147], v[184:187], v[16:19]
	ds_read_b128 v[250:253], v169 offset:7184
	v_mfma_f32_16x16x32_f16 v[20:23], v[132:135], v[188:191], v[20:23]
	v_mfma_f32_16x16x32_f16 v[24:27], v[136:139], v[188:191], v[24:27]
	v_mfma_f32_16x16x32_f16 v[28:31], v[140:143], v[188:191], v[28:31]
	v_mfma_f32_16x16x32_f16 v[32:35], v[144:147], v[188:191], v[32:35]
	v_mfma_f32_16x16x32_f16 v[36:39], v[132:135], v[192:195], v[36:39]
	v_mfma_f32_16x16x32_f16 v[40:43], v[136:139], v[192:195], v[40:43]
	v_mfma_f32_16x16x32_f16 v[44:47], v[140:143], v[192:195], v[44:47]
	v_mfma_f32_16x16x32_f16 v[48:51], v[144:147], v[192:195], v[48:51]
	v_mfma_f32_16x16x32_f16 v[52:55], v[132:135], v[196:199], v[52:55]
	v_mfma_f32_16x16x32_f16 v[56:59], v[136:139], v[196:199], v[56:59]
	v_mfma_f32_16x16x32_f16 v[60:63], v[140:143], v[196:199], v[60:63]
	v_mfma_f32_16x16x32_f16 v[64:67], v[144:147], v[196:199], v[64:67]
	s_waitcnt vmcnt(0) lgkmcnt(0)
	s_barrier
	s_add_i32 s37, s32, 0x8000
	s_cmp_lg_u32 s32, 0x18000
	s_cselect_b32 s37, s37, 0
	v_add_u32_e32 v168, s37, v165
	v_add_u32_e32 v169, s37, v164
	v_mfma_f32_16x16x32_f16 v[68:71], v[132:135], v[238:241], v[68:71]
	ds_read_b128 v[148:151], v168 offset:16
	ds_read_b128 v[184:187], v169 offset:16
	v_mfma_f32_16x16x32_f16 v[72:75], v[136:139], v[238:241], v[72:75]
	ds_read_b128 v[152:155], v168 offset:1040
	ds_read_b128 v[188:191], v169 offset:1040
	v_mfma_f32_16x16x32_f16 v[76:79], v[140:143], v[238:241], v[76:79]
	ds_read_b128 v[156:159], v168 offset:2064
	ds_read_b128 v[192:195], v169 offset:2064
	v_mfma_f32_16x16x32_f16 v[80:83], v[144:147], v[238:241], v[80:83]
	ds_read_b128 v[160:163], v168 offset:3088
	ds_read_b128 v[196:199], v169 offset:3088
	v_mfma_f32_16x16x32_f16 v[84:87], v[132:135], v[242:245], v[84:87]
	v_mfma_f32_16x16x32_f16 v[88:91], v[136:139], v[242:245], v[88:91]
	v_mfma_f32_16x16x32_f16 v[92:95], v[140:143], v[242:245], v[92:95]
	v_mfma_f32_16x16x32_f16 v[96:99], v[144:147], v[242:245], v[96:99]
	v_mfma_f32_16x16x32_f16 v[100:103], v[132:135], v[246:249], v[100:103]
	v_mfma_f32_16x16x32_f16 v[104:107], v[136:139], v[246:249], v[104:107]
	v_mfma_f32_16x16x32_f16 v[108:111], v[140:143], v[246:249], v[108:111]
	v_mfma_f32_16x16x32_f16 v[112:115], v[144:147], v[246:249], v[112:115]
	v_mfma_f32_16x16x32_f16 v[116:119], v[132:135], v[250:253], v[116:119]
	v_mfma_f32_16x16x32_f16 v[120:123], v[136:139], v[250:253], v[120:123]
	v_mfma_f32_16x16x32_f16 v[124:127], v[140:143], v[250:253], v[124:127]
	v_mfma_f32_16x16x32_f16 v[128:131], v[144:147], v[250:253], v[128:131]
	s_waitcnt lgkmcnt(0)
	s_mov_b32 s32, s37
	v_add_u32_e32 v169, s32, v164
	v_mfma_f32_16x16x32_f16 v[4:7], v[148:151], v[184:187], v[4:7]
	ds_read_b128 v[238:241], v169 offset:4112
	v_mfma_f32_16x16x32_f16 v[8:11], v[152:155], v[184:187], v[8:11]
	ds_read_b128 v[242:245], v169 offset:5136
	v_mfma_f32_16x16x32_f16 v[12:15], v[156:159], v[184:187], v[12:15]
	ds_read_b128 v[246:249], v169 offset:6160
	v_mfma_f32_16x16x32_f16 v[16:19], v[160:163], v[184:187], v[16:19]
	ds_read_b128 v[250:253], v169 offset:7184
	v_mfma_f32_16x16x32_f16 v[20:23], v[148:151], v[188:191], v[20:23]
	v_mfma_f32_16x16x32_f16 v[24:27], v[152:155], v[188:191], v[24:27]
	v_mfma_f32_16x16x32_f16 v[28:31], v[156:159], v[188:191], v[28:31]
	v_mfma_f32_16x16x32_f16 v[32:35], v[160:163], v[188:191], v[32:35]
	v_mfma_f32_16x16x32_f16 v[36:39], v[148:151], v[192:195], v[36:39]
	v_mfma_f32_16x16x32_f16 v[40:43], v[152:155], v[192:195], v[40:43]
	v_mfma_f32_16x16x32_f16 v[44:47], v[156:159], v[192:195], v[44:47]
	v_mfma_f32_16x16x32_f16 v[48:51], v[160:163], v[192:195], v[48:51]
	v_mfma_f32_16x16x32_f16 v[52:55], v[148:151], v[196:199], v[52:55]
	v_mfma_f32_16x16x32_f16 v[56:59], v[152:155], v[196:199], v[56:59]
	v_mfma_f32_16x16x32_f16 v[60:63], v[156:159], v[196:199], v[60:63]
	v_mfma_f32_16x16x32_f16 v[64:67], v[160:163], v[196:199], v[64:67]
	s_waitcnt lgkmcnt(0)
	s_barrier
	v_mfma_f32_16x16x32_f16 v[68:71], v[148:151], v[238:241], v[68:71]
	v_mfma_f32_16x16x32_f16 v[72:75], v[152:155], v[238:241], v[72:75]
	v_mfma_f32_16x16x32_f16 v[76:79], v[156:159], v[238:241], v[76:79]
	v_mfma_f32_16x16x32_f16 v[80:83], v[160:163], v[238:241], v[80:83]
	v_mfma_f32_16x16x32_f16 v[84:87], v[148:151], v[242:245], v[84:87]
	v_mfma_f32_16x16x32_f16 v[88:91], v[152:155], v[242:245], v[88:91]
	v_mfma_f32_16x16x32_f16 v[92:95], v[156:159], v[242:245], v[92:95]
	v_mfma_f32_16x16x32_f16 v[96:99], v[160:163], v[242:245], v[96:99]
	v_mfma_f32_16x16x32_f16 v[100:103], v[148:151], v[246:249], v[100:103]
	v_mfma_f32_16x16x32_f16 v[104:107], v[152:155], v[246:249], v[104:107]
	v_mfma_f32_16x16x32_f16 v[108:111], v[156:159], v[246:249], v[108:111]
	v_mfma_f32_16x16x32_f16 v[112:115], v[160:163], v[246:249], v[112:115]
	v_mfma_f32_16x16x32_f16 v[116:119], v[148:151], v[250:253], v[116:119]
	v_mfma_f32_16x16x32_f16 v[120:123], v[152:155], v[250:253], v[120:123]
	v_mfma_f32_16x16x32_f16 v[124:127], v[156:159], v[250:253], v[124:127]
	v_mfma_f32_16x16x32_f16 v[128:131], v[160:163], v[250:253], v[128:131]
	s_lshl_b64 s[80:81], s[28:29], 13
	s_add_u32 s80, s80, s34
	s_addc_u32 s81, s81, s35
	s_lshl_b32 s82, s65, 1
	s_add_u32 s80, s80, s82
	s_addc_u32 s81, s81, 0
	v_and_b32_e32 v172, 15, v200
	v_bfe_u32 v173, v200, 4, 2
	v_bfe_u32 v174, v200, 6, 2
	v_bfe_u32 v175, v200, 8, 1
	v_lshl_or_b32 v175, v175, 7, v172
	v_lshlrev_b32_e32 v175, 13, v175
	v_lshlrev_b32_e32 v174, 6, v174
	v_lshl_or_b32 v174, v173, 2, v174
	v_lshl_add_u32 v177, v174, 1, v175
	v_and_b32_e32 v172, 1, v173
	v_mul_u32_u24_e32 v172, 24, v172
	v_add_u32_e32 v177, v177, v172
	v_max_f32_e32 v4, 0, v4
	v_max_f32_e32 v5, 0, v5
	v_max_f32_e32 v6, 0, v6
	v_max_f32_e32 v7, 0, v7
	v_pk_mul_f32 v[4:5], v[4:5], v[4:5]
	v_pk_mul_f32 v[6:7], v[6:7], v[6:7]
	v_cvt_pk_f16_f32 v172, v4, v5
	v_cvt_pk_f16_f32 v173, v6, v7
	v_max_f32_e32 v8, 0, v8
	v_max_f32_e32 v9, 0, v9
	v_max_f32_e32 v10, 0, v10
	v_max_f32_e32 v11, 0, v11
	v_pk_mul_f32 v[8:9], v[8:9], v[8:9]
	v_pk_mul_f32 v[10:11], v[10:11], v[10:11]
	v_cvt_pk_f16_f32 v174, v8, v9
	v_cvt_pk_f16_f32 v175, v10, v11
	s_nop 1
	v_permlane16_swap_b32_e32 v172, v174
	v_permlane16_swap_b32_e32 v173, v175
	global_store_dwordx4 v177, v[172:175], s[80:81]
	v_max_f32_e32 v12, 0, v12
	v_max_f32_e32 v13, 0, v13
	v_max_f32_e32 v14, 0, v14
	v_max_f32_e32 v15, 0, v15
	v_pk_mul_f32 v[12:13], v[12:13], v[12:13]
	v_pk_mul_f32 v[14:15], v[14:15], v[14:15]
	v_cvt_pk_f16_f32 v228, v12, v13
	v_cvt_pk_f16_f32 v229, v14, v15
	v_max_f32_e32 v16, 0, v16
	v_max_f32_e32 v17, 0, v17
	v_max_f32_e32 v18, 0, v18
	v_max_f32_e32 v19, 0, v19
	v_pk_mul_f32 v[16:17], v[16:17], v[16:17]
	v_pk_mul_f32 v[18:19], v[18:19], v[18:19]
	v_cvt_pk_f16_f32 v230, v16, v17
	v_cvt_pk_f16_f32 v231, v18, v19
	s_nop 1
	v_permlane16_swap_b32_e32 v228, v230
	v_permlane16_swap_b32_e32 v229, v231
	global_store_dwordx4 v177, v[228:231], s[80:81] offset:64
	v_add_u32_e32 v177, 0x20000, v177
	v_max_f32_e32 v20, 0, v20
	v_max_f32_e32 v21, 0, v21
	v_max_f32_e32 v22, 0, v22
	v_max_f32_e32 v23, 0, v23
	v_pk_mul_f32 v[20:21], v[20:21], v[20:21]
	v_pk_mul_f32 v[22:23], v[22:23], v[22:23]
	v_cvt_pk_f16_f32 v172, v20, v21
	v_cvt_pk_f16_f32 v173, v22, v23
	v_max_f32_e32 v24, 0, v24
	v_max_f32_e32 v25, 0, v25
	v_max_f32_e32 v26, 0, v26
	v_max_f32_e32 v27, 0, v27
	v_pk_mul_f32 v[24:25], v[24:25], v[24:25]
	v_pk_mul_f32 v[26:27], v[26:27], v[26:27]
	v_cvt_pk_f16_f32 v174, v24, v25
	v_cvt_pk_f16_f32 v175, v26, v27
	s_nop 1
	v_permlane16_swap_b32_e32 v172, v174
	v_permlane16_swap_b32_e32 v173, v175
	global_store_dwordx4 v177, v[172:175], s[80:81]
	v_max_f32_e32 v28, 0, v28
	v_max_f32_e32 v29, 0, v29
	v_max_f32_e32 v30, 0, v30
	v_max_f32_e32 v31, 0, v31
	v_pk_mul_f32 v[28:29], v[28:29], v[28:29]
	v_pk_mul_f32 v[30:31], v[30:31], v[30:31]
	v_cvt_pk_f16_f32 v228, v28, v29
	v_cvt_pk_f16_f32 v229, v30, v31
	v_max_f32_e32 v32, 0, v32
	v_max_f32_e32 v33, 0, v33
	v_max_f32_e32 v34, 0, v34
	v_max_f32_e32 v35, 0, v35
	v_pk_mul_f32 v[32:33], v[32:33], v[32:33]
	v_pk_mul_f32 v[34:35], v[34:35], v[34:35]
	v_cvt_pk_f16_f32 v230, v32, v33
	v_cvt_pk_f16_f32 v231, v34, v35
	s_nop 1
	v_permlane16_swap_b32_e32 v228, v230
	v_permlane16_swap_b32_e32 v229, v231
	global_store_dwordx4 v177, v[228:231], s[80:81] offset:64
	v_add_u32_e32 v177, 0x20000, v177
	v_max_f32_e32 v36, 0, v36
	v_max_f32_e32 v37, 0, v37
	v_max_f32_e32 v38, 0, v38
	v_max_f32_e32 v39, 0, v39
	v_pk_mul_f32 v[36:37], v[36:37], v[36:37]
	v_pk_mul_f32 v[38:39], v[38:39], v[38:39]
	v_cvt_pk_f16_f32 v172, v36, v37
	v_cvt_pk_f16_f32 v173, v38, v39
	v_max_f32_e32 v40, 0, v40
	v_max_f32_e32 v41, 0, v41
	v_max_f32_e32 v42, 0, v42
	v_max_f32_e32 v43, 0, v43
	v_pk_mul_f32 v[40:41], v[40:41], v[40:41]
	v_pk_mul_f32 v[42:43], v[42:43], v[42:43]
	v_cvt_pk_f16_f32 v174, v40, v41
	v_cvt_pk_f16_f32 v175, v42, v43
	s_nop 1
	v_permlane16_swap_b32_e32 v172, v174
	v_permlane16_swap_b32_e32 v173, v175
	global_store_dwordx4 v177, v[172:175], s[80:81]
	v_max_f32_e32 v44, 0, v44
	v_max_f32_e32 v45, 0, v45
	v_max_f32_e32 v46, 0, v46
	v_max_f32_e32 v47, 0, v47
	v_pk_mul_f32 v[44:45], v[44:45], v[44:45]
	v_pk_mul_f32 v[46:47], v[46:47], v[46:47]
	v_cvt_pk_f16_f32 v228, v44, v45
	v_cvt_pk_f16_f32 v229, v46, v47
	v_max_f32_e32 v48, 0, v48
	v_max_f32_e32 v49, 0, v49
	v_max_f32_e32 v50, 0, v50
	v_max_f32_e32 v51, 0, v51
	v_pk_mul_f32 v[48:49], v[48:49], v[48:49]
	v_pk_mul_f32 v[50:51], v[50:51], v[50:51]
	v_cvt_pk_f16_f32 v230, v48, v49
	v_cvt_pk_f16_f32 v231, v50, v51
	s_nop 1
	v_permlane16_swap_b32_e32 v228, v230
	v_permlane16_swap_b32_e32 v229, v231
	global_store_dwordx4 v177, v[228:231], s[80:81] offset:64
	v_add_u32_e32 v177, 0x20000, v177
	v_max_f32_e32 v52, 0, v52
	v_max_f32_e32 v53, 0, v53
	v_max_f32_e32 v54, 0, v54
	v_max_f32_e32 v55, 0, v55
	v_pk_mul_f32 v[52:53], v[52:53], v[52:53]
	v_pk_mul_f32 v[54:55], v[54:55], v[54:55]
	v_cvt_pk_f16_f32 v172, v52, v53
	v_cvt_pk_f16_f32 v173, v54, v55
	v_max_f32_e32 v56, 0, v56
	v_max_f32_e32 v57, 0, v57
	v_max_f32_e32 v58, 0, v58
	v_max_f32_e32 v59, 0, v59
	v_pk_mul_f32 v[56:57], v[56:57], v[56:57]
	v_pk_mul_f32 v[58:59], v[58:59], v[58:59]
	v_cvt_pk_f16_f32 v174, v56, v57
	v_cvt_pk_f16_f32 v175, v58, v59
	s_nop 1
	v_permlane16_swap_b32_e32 v172, v174
	v_permlane16_swap_b32_e32 v173, v175
	global_store_dwordx4 v177, v[172:175], s[80:81]
	v_max_f32_e32 v60, 0, v60
	v_max_f32_e32 v61, 0, v61
	v_max_f32_e32 v62, 0, v62
	v_max_f32_e32 v63, 0, v63
	v_pk_mul_f32 v[60:61], v[60:61], v[60:61]
	v_pk_mul_f32 v[62:63], v[62:63], v[62:63]
	v_cvt_pk_f16_f32 v228, v60, v61
	v_cvt_pk_f16_f32 v229, v62, v63
	v_max_f32_e32 v64, 0, v64
	v_max_f32_e32 v65, 0, v65
	v_max_f32_e32 v66, 0, v66
	v_max_f32_e32 v67, 0, v67
	v_pk_mul_f32 v[64:65], v[64:65], v[64:65]
	v_pk_mul_f32 v[66:67], v[66:67], v[66:67]
	v_cvt_pk_f16_f32 v230, v64, v65
	v_cvt_pk_f16_f32 v231, v66, v67
	s_nop 1
	v_permlane16_swap_b32_e32 v228, v230
	v_permlane16_swap_b32_e32 v229, v231
	global_store_dwordx4 v177, v[228:231], s[80:81] offset:64
	v_add_u32_e32 v177, 0x20000, v177
	v_max_f32_e32 v68, 0, v68
	v_max_f32_e32 v69, 0, v69
	v_max_f32_e32 v70, 0, v70
	v_max_f32_e32 v71, 0, v71
	v_pk_mul_f32 v[68:69], v[68:69], v[68:69]
	v_pk_mul_f32 v[70:71], v[70:71], v[70:71]
	v_cvt_pk_f16_f32 v172, v68, v69
	v_cvt_pk_f16_f32 v173, v70, v71
	v_max_f32_e32 v72, 0, v72
	v_max_f32_e32 v73, 0, v73
	v_max_f32_e32 v74, 0, v74
	v_max_f32_e32 v75, 0, v75
	v_pk_mul_f32 v[72:73], v[72:73], v[72:73]
	v_pk_mul_f32 v[74:75], v[74:75], v[74:75]
	v_cvt_pk_f16_f32 v174, v72, v73
	v_cvt_pk_f16_f32 v175, v74, v75
	s_nop 1
	v_permlane16_swap_b32_e32 v172, v174
	v_permlane16_swap_b32_e32 v173, v175
	global_store_dwordx4 v177, v[172:175], s[80:81]
	v_max_f32_e32 v76, 0, v76
	v_max_f32_e32 v77, 0, v77
	v_max_f32_e32 v78, 0, v78
	v_max_f32_e32 v79, 0, v79
	v_pk_mul_f32 v[76:77], v[76:77], v[76:77]
	v_pk_mul_f32 v[78:79], v[78:79], v[78:79]
	v_cvt_pk_f16_f32 v228, v76, v77
	v_cvt_pk_f16_f32 v229, v78, v79
	v_max_f32_e32 v80, 0, v80
	v_max_f32_e32 v81, 0, v81
	v_max_f32_e32 v82, 0, v82
	v_max_f32_e32 v83, 0, v83
	v_pk_mul_f32 v[80:81], v[80:81], v[80:81]
	v_pk_mul_f32 v[82:83], v[82:83], v[82:83]
	v_cvt_pk_f16_f32 v230, v80, v81
	v_cvt_pk_f16_f32 v231, v82, v83
	s_nop 1
	v_permlane16_swap_b32_e32 v228, v230
	v_permlane16_swap_b32_e32 v229, v231
	global_store_dwordx4 v177, v[228:231], s[80:81] offset:64
	v_add_u32_e32 v177, 0x20000, v177
	v_max_f32_e32 v84, 0, v84
	v_max_f32_e32 v85, 0, v85
	v_max_f32_e32 v86, 0, v86
	v_max_f32_e32 v87, 0, v87
	v_pk_mul_f32 v[84:85], v[84:85], v[84:85]
	v_pk_mul_f32 v[86:87], v[86:87], v[86:87]
	v_cvt_pk_f16_f32 v172, v84, v85
	v_cvt_pk_f16_f32 v173, v86, v87
	v_max_f32_e32 v88, 0, v88
	v_max_f32_e32 v89, 0, v89
	v_max_f32_e32 v90, 0, v90
	v_max_f32_e32 v91, 0, v91
	v_pk_mul_f32 v[88:89], v[88:89], v[88:89]
	v_pk_mul_f32 v[90:91], v[90:91], v[90:91]
	v_cvt_pk_f16_f32 v174, v88, v89
	v_cvt_pk_f16_f32 v175, v90, v91
	s_nop 1
	v_permlane16_swap_b32_e32 v172, v174
	v_permlane16_swap_b32_e32 v173, v175
	global_store_dwordx4 v177, v[172:175], s[80:81]
	v_max_f32_e32 v92, 0, v92
	v_max_f32_e32 v93, 0, v93
	v_max_f32_e32 v94, 0, v94
	v_max_f32_e32 v95, 0, v95
	v_pk_mul_f32 v[92:93], v[92:93], v[92:93]
	v_pk_mul_f32 v[94:95], v[94:95], v[94:95]
	v_cvt_pk_f16_f32 v228, v92, v93
	v_cvt_pk_f16_f32 v229, v94, v95
	v_max_f32_e32 v96, 0, v96
	v_max_f32_e32 v97, 0, v97
	v_max_f32_e32 v98, 0, v98
	v_max_f32_e32 v99, 0, v99
	v_pk_mul_f32 v[96:97], v[96:97], v[96:97]
	v_pk_mul_f32 v[98:99], v[98:99], v[98:99]
	v_cvt_pk_f16_f32 v230, v96, v97
	v_cvt_pk_f16_f32 v231, v98, v99
	s_nop 1
	v_permlane16_swap_b32_e32 v228, v230
	v_permlane16_swap_b32_e32 v229, v231
	global_store_dwordx4 v177, v[228:231], s[80:81] offset:64
	v_add_u32_e32 v177, 0x20000, v177
	v_max_f32_e32 v100, 0, v100
	v_max_f32_e32 v101, 0, v101
	v_max_f32_e32 v102, 0, v102
	v_max_f32_e32 v103, 0, v103
	v_pk_mul_f32 v[100:101], v[100:101], v[100:101]
	v_pk_mul_f32 v[102:103], v[102:103], v[102:103]
	v_cvt_pk_f16_f32 v172, v100, v101
	v_cvt_pk_f16_f32 v173, v102, v103
	v_max_f32_e32 v104, 0, v104
	v_max_f32_e32 v105, 0, v105
	v_max_f32_e32 v106, 0, v106
	v_max_f32_e32 v107, 0, v107
	v_pk_mul_f32 v[104:105], v[104:105], v[104:105]
	v_pk_mul_f32 v[106:107], v[106:107], v[106:107]
	v_cvt_pk_f16_f32 v174, v104, v105
	v_cvt_pk_f16_f32 v175, v106, v107
	s_nop 1
	v_permlane16_swap_b32_e32 v172, v174
	v_permlane16_swap_b32_e32 v173, v175
	global_store_dwordx4 v177, v[172:175], s[80:81]
	v_max_f32_e32 v108, 0, v108
	v_max_f32_e32 v109, 0, v109
	v_max_f32_e32 v110, 0, v110
	v_max_f32_e32 v111, 0, v111
	v_pk_mul_f32 v[108:109], v[108:109], v[108:109]
	v_pk_mul_f32 v[110:111], v[110:111], v[110:111]
	v_cvt_pk_f16_f32 v228, v108, v109
	v_cvt_pk_f16_f32 v229, v110, v111
	v_max_f32_e32 v112, 0, v112
	v_max_f32_e32 v113, 0, v113
	v_max_f32_e32 v114, 0, v114
	v_max_f32_e32 v115, 0, v115
	v_pk_mul_f32 v[112:113], v[112:113], v[112:113]
	v_pk_mul_f32 v[114:115], v[114:115], v[114:115]
	v_cvt_pk_f16_f32 v230, v112, v113
	v_cvt_pk_f16_f32 v231, v114, v115
	s_nop 1
	v_permlane16_swap_b32_e32 v228, v230
	v_permlane16_swap_b32_e32 v229, v231
	global_store_dwordx4 v177, v[228:231], s[80:81] offset:64
	v_add_u32_e32 v177, 0x20000, v177
	v_max_f32_e32 v116, 0, v116
	v_max_f32_e32 v117, 0, v117
	v_max_f32_e32 v118, 0, v118
	v_max_f32_e32 v119, 0, v119
	v_pk_mul_f32 v[116:117], v[116:117], v[116:117]
	v_pk_mul_f32 v[118:119], v[118:119], v[118:119]
	v_cvt_pk_f16_f32 v172, v116, v117
	v_cvt_pk_f16_f32 v173, v118, v119
	v_max_f32_e32 v120, 0, v120
	v_max_f32_e32 v121, 0, v121
	v_max_f32_e32 v122, 0, v122
	v_max_f32_e32 v123, 0, v123
	v_pk_mul_f32 v[120:121], v[120:121], v[120:121]
	v_pk_mul_f32 v[122:123], v[122:123], v[122:123]
	v_cvt_pk_f16_f32 v174, v120, v121
	v_cvt_pk_f16_f32 v175, v122, v123
	s_nop 1
	v_permlane16_swap_b32_e32 v172, v174
	v_permlane16_swap_b32_e32 v173, v175
	global_store_dwordx4 v177, v[172:175], s[80:81]
	v_max_f32_e32 v124, 0, v124
	v_max_f32_e32 v125, 0, v125
	v_max_f32_e32 v126, 0, v126
	v_max_f32_e32 v127, 0, v127
	v_pk_mul_f32 v[124:125], v[124:125], v[124:125]
	v_pk_mul_f32 v[126:127], v[126:127], v[126:127]
	v_cvt_pk_f16_f32 v228, v124, v125
	v_cvt_pk_f16_f32 v229, v126, v127
	v_max_f32_e32 v128, 0, v128
	v_max_f32_e32 v129, 0, v129
	v_max_f32_e32 v130, 0, v130
	v_max_f32_e32 v131, 0, v131
	v_pk_mul_f32 v[128:129], v[128:129], v[128:129]
	v_pk_mul_f32 v[130:131], v[130:131], v[130:131]
	v_cvt_pk_f16_f32 v230, v128, v129
	v_cvt_pk_f16_f32 v231, v130, v131
	s_nop 1
	v_permlane16_swap_b32_e32 v228, v230
	v_permlane16_swap_b32_e32 v229, v231
	global_store_dwordx4 v177, v[228:231], s[80:81] offset:64
	s_nop 1
	s_add_i32 s56, s56, s76
	s_cmp_ge_i32 s56, s58
	s_cbranch_scc1 .LBB0_127
	s_branch .LBB0_111

.Lt_mlp1a:
	v_add_u32_e32 v169, s37, v164
	v_mfma_f32_16x16x32_f16 v[4:7], v[132:135], v[184:187], v[4:7]
	ds_read_b128 v[238:241], v169 offset:4112
	v_mfma_f32_16x16x32_f16 v[8:11], v[136:139], v[184:187], v[8:11]
	ds_read_b128 v[242:245], v169 offset:5136
	v_mfma_f32_16x16x32_f16 v[12:15], v[140:143], v[184:187], v[12:15]
	ds_read_b128 v[246:249], v169 offset:6160
	v_mfma_f32_16x16x32_f16 v[16:19], v[144:147], v[184:187], v[16:19]
	ds_read_b128 v[250:253], v169 offset:7184
	v_mfma_f32_16x16x32_f16 v[20:23], v[132:135], v[188:191], v[20:23]
	v_mfma_f32_16x16x32_f16 v[24:27], v[136:139], v[188:191], v[24:27]
	v_mfma_f32_16x16x32_f16 v[28:31], v[140:143], v[188:191], v[28:31]
	v_mfma_f32_16x16x32_f16 v[32:35], v[144:147], v[188:191], v[32:35]
	v_mfma_f32_16x16x32_f16 v[36:39], v[132:135], v[192:195], v[36:39]
	v_mfma_f32_16x16x32_f16 v[40:43], v[136:139], v[192:195], v[40:43]
	v_mfma_f32_16x16x32_f16 v[44:47], v[140:143], v[192:195], v[44:47]
	v_mfma_f32_16x16x32_f16 v[48:51], v[144:147], v[192:195], v[48:51]
	v_mfma_f32_16x16x32_f16 v[52:55], v[132:135], v[196:199], v[52:55]
	v_mfma_f32_16x16x32_f16 v[56:59], v[136:139], v[196:199], v[56:59]
	v_mfma_f32_16x16x32_f16 v[60:63], v[140:143], v[196:199], v[60:63]
	v_mfma_f32_16x16x32_f16 v[64:67], v[144:147], v[196:199], v[64:67]
	s_waitcnt vmcnt(8) lgkmcnt(0)
	s_barrier
	s_add_i32 s53, s37, 0x8000
	s_cmp_lg_u32 s37, 0x18000
	s_cselect_b32 s53, s53, 0
	v_add_u32_e32 v168, s53, v165
	v_add_u32_e32 v169, s53, v164
	s_add_u32 vcc_lo, s32, s37
	v_mfma_f32_16x16x32_f16 v[68:71], v[132:135], v[238:241], v[68:71]
	ds_read_b128 v[148:151], v168 offset:16
	ds_read_b128 v[184:187], v169 offset:16
	v_mfma_f32_16x16x32_f16 v[72:75], v[136:139], v[238:241], v[72:75]
	ds_read_b128 v[152:155], v168 offset:1040
	ds_read_b128 v[188:191], v169 offset:1040
	v_mfma_f32_16x16x32_f16 v[76:79], v[140:143], v[238:241], v[76:79]
	ds_read_b128 v[156:159], v168 offset:2064
	ds_read_b128 v[192:195], v169 offset:2064
	v_mfma_f32_16x16x32_f16 v[80:83], v[144:147], v[238:241], v[80:83]
	ds_read_b128 v[160:163], v168 offset:3088
	ds_read_b128 v[196:199], v169 offset:3088
	v_mfma_f32_16x16x32_f16 v[84:87], v[132:135], v[242:245], v[84:87]
	v_mfma_f32_16x16x32_f16 v[88:91], v[136:139], v[242:245], v[88:91]
	v_mfma_f32_16x16x32_f16 v[92:95], v[140:143], v[242:245], v[92:95]
	v_mfma_f32_16x16x32_f16 v[96:99], v[144:147], v[242:245], v[96:99]
	v_mfma_f32_16x16x32_f16 v[100:103], v[132:135], v[246:249], v[100:103]
	s_mov_b32 m0, vcc_lo
	s_nop 0
	global_load_lds_dwordx4 v170, s[30:31]
	v_mfma_f32_16x16x32_f16 v[104:107], v[136:139], v[246:249], v[104:107]
	s_add_u32 m0, vcc_lo, 0x400
	s_nop 0
	global_load_lds_dwordx4 v171, s[30:31]
	v_mfma_f32_16x16x32_f16 v[108:111], v[140:143], v[246:249], v[108:111]
	s_add_u32 m0, vcc_lo, 0x4000
	s_nop 0
	global_load_lds_dwordx4 v170, s[56:57]
	v_mfma_f32_16x16x32_f16 v[112:115], v[144:147], v[246:249], v[112:115]
	s_add_u32 m0, vcc_lo, 0x4400
	s_nop 0
	global_load_lds_dwordx4 v171, s[56:57]
	v_mfma_f32_16x16x32_f16 v[116:119], v[132:135], v[250:253], v[116:119]
	v_mfma_f32_16x16x32_f16 v[120:123], v[136:139], v[250:253], v[120:123]
	v_mfma_f32_16x16x32_f16 v[124:127], v[140:143], v[250:253], v[124:127]
	v_mfma_f32_16x16x32_f16 v[128:131], v[144:147], v[250:253], v[128:131]
	s_waitcnt lgkmcnt(0)
	s_mov_b32 s37, s53
	s_add_u32 s30, s30, 64
	s_addc_u32 s31, s31, 0
	s_add_u32 s56, s56, 64
	s_addc_u32 s57, s57, 0
	v_add_u32_e32 v169, s37, v164
	v_mfma_f32_16x16x32_f16 v[4:7], v[148:151], v[184:187], v[4:7]
	ds_read_b128 v[238:241], v169 offset:4112
	v_mfma_f32_16x16x32_f16 v[8:11], v[152:155], v[184:187], v[8:11]
	ds_read_b128 v[242:245], v169 offset:5136
	v_mfma_f32_16x16x32_f16 v[12:15], v[156:159], v[184:187], v[12:15]
	ds_read_b128 v[246:249], v169 offset:6160
	v_mfma_f32_16x16x32_f16 v[16:19], v[160:163], v[184:187], v[16:19]
	ds_read_b128 v[250:253], v169 offset:7184
	v_mfma_f32_16x16x32_f16 v[20:23], v[148:151], v[188:191], v[20:23]
	v_mfma_f32_16x16x32_f16 v[24:27], v[152:155], v[188:191], v[24:27]
	v_mfma_f32_16x16x32_f16 v[28:31], v[156:159], v[188:191], v[28:31]
	v_mfma_f32_16x16x32_f16 v[32:35], v[160:163], v[188:191], v[32:35]
	v_mfma_f32_16x16x32_f16 v[36:39], v[148:151], v[192:195], v[36:39]
	v_mfma_f32_16x16x32_f16 v[40:43], v[152:155], v[192:195], v[40:43]
	v_mfma_f32_16x16x32_f16 v[44:47], v[156:159], v[192:195], v[44:47]
	v_mfma_f32_16x16x32_f16 v[48:51], v[160:163], v[192:195], v[48:51]
	v_mfma_f32_16x16x32_f16 v[52:55], v[148:151], v[196:199], v[52:55]
	v_mfma_f32_16x16x32_f16 v[56:59], v[152:155], v[196:199], v[56:59]
	v_mfma_f32_16x16x32_f16 v[60:63], v[156:159], v[196:199], v[60:63]
	v_mfma_f32_16x16x32_f16 v[64:67], v[160:163], v[196:199], v[64:67]
	s_waitcnt vmcnt(8) lgkmcnt(0)
	s_barrier
	s_add_i32 s53, s37, 0x8000
	s_cmp_lg_u32 s37, 0x18000
	s_cselect_b32 s53, s53, 0
	v_add_u32_e32 v168, s53, v165
	v_add_u32_e32 v169, s53, v164
	s_add_u32 vcc_lo, s32, s37
	v_mfma_f32_16x16x32_f16 v[68:71], v[148:151], v[238:241], v[68:71]
	ds_read_b128 v[132:135], v168 offset:16
	ds_read_b128 v[184:187], v169 offset:16
	v_mfma_f32_16x16x32_f16 v[72:75], v[152:155], v[238:241], v[72:75]
	ds_read_b128 v[136:139], v168 offset:1040
	ds_read_b128 v[188:191], v169 offset:1040
	v_mfma_f32_16x16x32_f16 v[76:79], v[156:159], v[238:241], v[76:79]
	ds_read_b128 v[140:143], v168 offset:2064
	ds_read_b128 v[192:195], v169 offset:2064
	v_mfma_f32_16x16x32_f16 v[80:83], v[160:163], v[238:241], v[80:83]
	ds_read_b128 v[144:147], v168 offset:3088
	ds_read_b128 v[196:199], v169 offset:3088
	v_mfma_f32_16x16x32_f16 v[84:87], v[148:151], v[242:245], v[84:87]
	v_mfma_f32_16x16x32_f16 v[88:91], v[152:155], v[242:245], v[88:91]
	v_mfma_f32_16x16x32_f16 v[92:95], v[156:159], v[242:245], v[92:95]
	v_mfma_f32_16x16x32_f16 v[96:99], v[160:163], v[242:245], v[96:99]
	v_mfma_f32_16x16x32_f16 v[100:103], v[148:151], v[246:249], v[100:103]
	s_mov_b32 m0, vcc_lo
	s_nop 0
	global_load_lds_dwordx4 v170, s[30:31]
	v_mfma_f32_16x16x32_f16 v[104:107], v[152:155], v[246:249], v[104:107]
	s_add_u32 m0, vcc_lo, 0x400
	s_nop 0
	global_load_lds_dwordx4 v171, s[30:31]
	v_mfma_f32_16x16x32_f16 v[108:111], v[156:159], v[246:249], v[108:111]
	s_add_u32 m0, vcc_lo, 0x4000
	s_nop 0
	global_load_lds_dwordx4 v170, s[56:57]
	v_mfma_f32_16x16x32_f16 v[112:115], v[160:163], v[246:249], v[112:115]
	s_add_u32 m0, vcc_lo, 0x4400
	s_nop 0
	global_load_lds_dwordx4 v171, s[56:57]
	v_mfma_f32_16x16x32_f16 v[116:119], v[148:151], v[250:253], v[116:119]
	v_mfma_f32_16x16x32_f16 v[120:123], v[152:155], v[250:253], v[120:123]
	v_mfma_f32_16x16x32_f16 v[124:127], v[156:159], v[250:253], v[124:127]
	v_mfma_f32_16x16x32_f16 v[128:131], v[160:163], v[250:253], v[128:131]
	s_waitcnt lgkmcnt(0)
	s_mov_b32 s37, s53
	s_add_u32 s30, s30, 64
	s_addc_u32 s31, s31, 0
	s_add_u32 s56, s56, 64
	s_addc_u32 s57, s57, 0
	s_add_i32 s55, s55, 2
	s_cmp_lt_u32 s55, 28
	s_cbranch_scc1 .Lt_mlp1a
	v_add_u32_e32 v169, s37, v164
	v_mfma_f32_16x16x32_f16 v[4:7], v[132:135], v[184:187], v[4:7]
	ds_read_b128 v[238:241], v169 offset:4112
	v_mfma_f32_16x16x32_f16 v[8:11], v[136:139], v[184:187], v[8:11]
	ds_read_b128 v[242:245], v169 offset:5136
	v_mfma_f32_16x16x32_f16 v[12:15], v[140:143], v[184:187], v[12:15]
	ds_read_b128 v[246:249], v169 offset:6160
	v_mfma_f32_16x16x32_f16 v[16:19], v[144:147], v[184:187], v[16:19]
	ds_read_b128 v[250:253], v169 offset:7184
	v_mfma_f32_16x16x32_f16 v[20:23], v[132:135], v[188:191], v[20:23]
	v_mfma_f32_16x16x32_f16 v[24:27], v[136:139], v[188:191], v[24:27]
	v_mfma_f32_16x16x32_f16 v[28:31], v[140:143], v[188:191], v[28:31]
	v_mfma_f32_16x16x32_f16 v[32:35], v[144:147], v[188:191], v[32:35]
	v_mfma_f32_16x16x32_f16 v[36:39], v[132:135], v[192:195], v[36:39]
	v_mfma_f32_16x16x32_f16 v[40:43], v[136:139], v[192:195], v[40:43]
	v_mfma_f32_16x16x32_f16 v[44:47], v[140:143], v[192:195], v[44:47]
	v_mfma_f32_16x16x32_f16 v[48:51], v[144:147], v[192:195], v[48:51]
	v_mfma_f32_16x16x32_f16 v[52:55], v[132:135], v[196:199], v[52:55]
	v_mfma_f32_16x16x32_f16 v[56:59], v[136:139], v[196:199], v[56:59]
	v_mfma_f32_16x16x32_f16 v[60:63], v[140:143], v[196:199], v[60:63]
	v_mfma_f32_16x16x32_f16 v[64:67], v[144:147], v[196:199], v[64:67]
	s_waitcnt vmcnt(8) lgkmcnt(0)
	s_barrier
	s_add_i32 s53, s37, 0x8000
	s_cmp_lg_u32 s37, 0x18000
	s_cselect_b32 s53, s53, 0
	v_add_u32_e32 v168, s53, v165
	v_add_u32_e32 v169, s53, v164
	v_mfma_f32_16x16x32_f16 v[68:71], v[132:135], v[238:241], v[68:71]
	ds_read_b128 v[148:151], v168 offset:16
	ds_read_b128 v[184:187], v169 offset:16
	v_mfma_f32_16x16x32_f16 v[72:75], v[136:139], v[238:241], v[72:75]
	ds_read_b128 v[152:155], v168 offset:1040
	ds_read_b128 v[188:191], v169 offset:1040
	v_mfma_f32_16x16x32_f16 v[76:79], v[140:143], v[238:241], v[76:79]
	ds_read_b128 v[156:159], v168 offset:2064
	ds_read_b128 v[192:195], v169 offset:2064
	v_mfma_f32_16x16x32_f16 v[80:83], v[144:147], v[238:241], v[80:83]
	ds_read_b128 v[160:163], v168 offset:3088
	ds_read_b128 v[196:199], v169 offset:3088
	v_mfma_f32_16x16x32_f16 v[84:87], v[132:135], v[242:245], v[84:87]
	v_mfma_f32_16x16x32_f16 v[88:91], v[136:139], v[242:245], v[88:91]
	v_mfma_f32_16x16x32_f16 v[92:95], v[140:143], v[242:245], v[92:95]
	v_mfma_f32_16x16x32_f16 v[96:99], v[144:147], v[242:245], v[96:99]
	v_mfma_f32_16x16x32_f16 v[100:103], v[132:135], v[246:249], v[100:103]
	v_mfma_f32_16x16x32_f16 v[104:107], v[136:139], v[246:249], v[104:107]
	v_mfma_f32_16x16x32_f16 v[108:111], v[140:143], v[246:249], v[108:111]
	v_mfma_f32_16x16x32_f16 v[112:115], v[144:147], v[246:249], v[112:115]
	v_mfma_f32_16x16x32_f16 v[116:119], v[132:135], v[250:253], v[116:119]
	v_mfma_f32_16x16x32_f16 v[120:123], v[136:139], v[250:253], v[120:123]
	v_mfma_f32_16x16x32_f16 v[124:127], v[140:143], v[250:253], v[124:127]
	v_mfma_f32_16x16x32_f16 v[128:131], v[144:147], v[250:253], v[128:131]
	s_waitcnt lgkmcnt(0)
	s_mov_b32 s37, s53
	v_add_u32_e32 v169, s37, v164
	v_mfma_f32_16x16x32_f16 v[4:7], v[148:151], v[184:187], v[4:7]
	ds_read_b128 v[238:241], v169 offset:4112
	v_mfma_f32_16x16x32_f16 v[8:11], v[152:155], v[184:187], v[8:11]
	ds_read_b128 v[242:245], v169 offset:5136
	v_mfma_f32_16x16x32_f16 v[12:15], v[156:159], v[184:187], v[12:15]
	ds_read_b128 v[246:249], v169 offset:6160
	v_mfma_f32_16x16x32_f16 v[16:19], v[160:163], v[184:187], v[16:19]
	ds_read_b128 v[250:253], v169 offset:7184
	v_mfma_f32_16x16x32_f16 v[20:23], v[148:151], v[188:191], v[20:23]
	v_mfma_f32_16x16x32_f16 v[24:27], v[152:155], v[188:191], v[24:27]
	v_mfma_f32_16x16x32_f16 v[28:31], v[156:159], v[188:191], v[28:31]
	v_mfma_f32_16x16x32_f16 v[32:35], v[160:163], v[188:191], v[32:35]
	v_mfma_f32_16x16x32_f16 v[36:39], v[148:151], v[192:195], v[36:39]
	v_mfma_f32_16x16x32_f16 v[40:43], v[152:155], v[192:195], v[40:43]
	v_mfma_f32_16x16x32_f16 v[44:47], v[156:159], v[192:195], v[44:47]
	v_mfma_f32_16x16x32_f16 v[48:51], v[160:163], v[192:195], v[48:51]
	v_mfma_f32_16x16x32_f16 v[52:55], v[148:151], v[196:199], v[52:55]
	v_mfma_f32_16x16x32_f16 v[56:59], v[152:155], v[196:199], v[56:59]
	v_mfma_f32_16x16x32_f16 v[60:63], v[156:159], v[196:199], v[60:63]
	v_mfma_f32_16x16x32_f16 v[64:67], v[160:163], v[196:199], v[64:67]
	s_waitcnt vmcnt(4) lgkmcnt(0)
	s_barrier
	s_add_i32 s53, s37, 0x8000
	s_cmp_lg_u32 s37, 0x18000
	s_cselect_b32 s53, s53, 0
	v_add_u32_e32 v168, s53, v165
	v_add_u32_e32 v169, s53, v164
	v_mfma_f32_16x16x32_f16 v[68:71], v[148:151], v[238:241], v[68:71]
	ds_read_b128 v[132:135], v168 offset:16
	ds_read_b128 v[184:187], v169 offset:16
	v_mfma_f32_16x16x32_f16 v[72:75], v[152:155], v[238:241], v[72:75]
	ds_read_b128 v[136:139], v168 offset:1040
	ds_read_b128 v[188:191], v169 offset:1040
	v_mfma_f32_16x16x32_f16 v[76:79], v[156:159], v[238:241], v[76:79]
	ds_read_b128 v[140:143], v168 offset:2064
	ds_read_b128 v[192:195], v169 offset:2064
	v_mfma_f32_16x16x32_f16 v[80:83], v[160:163], v[238:241], v[80:83]
	ds_read_b128 v[144:147], v168 offset:3088
	ds_read_b128 v[196:199], v169 offset:3088
	v_mfma_f32_16x16x32_f16 v[84:87], v[148:151], v[242:245], v[84:87]
	v_mfma_f32_16x16x32_f16 v[88:91], v[152:155], v[242:245], v[88:91]
	v_mfma_f32_16x16x32_f16 v[92:95], v[156:159], v[242:245], v[92:95]
	v_mfma_f32_16x16x32_f16 v[96:99], v[160:163], v[242:245], v[96:99]
	v_mfma_f32_16x16x32_f16 v[100:103], v[148:151], v[246:249], v[100:103]
	v_mfma_f32_16x16x32_f16 v[104:107], v[152:155], v[246:249], v[104:107]
	v_mfma_f32_16x16x32_f16 v[108:111], v[156:159], v[246:249], v[108:111]
	v_mfma_f32_16x16x32_f16 v[112:115], v[160:163], v[246:249], v[112:115]
	v_mfma_f32_16x16x32_f16 v[116:119], v[148:151], v[250:253], v[116:119]
	v_mfma_f32_16x16x32_f16 v[120:123], v[152:155], v[250:253], v[120:123]
	v_mfma_f32_16x16x32_f16 v[124:127], v[156:159], v[250:253], v[124:127]
	v_mfma_f32_16x16x32_f16 v[128:131], v[160:163], v[250:253], v[128:131]
	s_waitcnt lgkmcnt(0)
	s_mov_b32 s37, s53
	v_add_u32_e32 v169, s37, v164
	v_mfma_f32_16x16x32_f16 v[4:7], v[132:135], v[184:187], v[4:7]
	ds_read_b128 v[238:241], v169 offset:4112
	v_mfma_f32_16x16x32_f16 v[8:11], v[136:139], v[184:187], v[8:11]
	ds_read_b128 v[242:245], v169 offset:5136
	v_mfma_f32_16x16x32_f16 v[12:15], v[140:143], v[184:187], v[12:15]
	ds_read_b128 v[246:249], v169 offset:6160
	v_mfma_f32_16x16x32_f16 v[16:19], v[144:147], v[184:187], v[16:19]
	ds_read_b128 v[250:253], v169 offset:7184
	v_mfma_f32_16x16x32_f16 v[20:23], v[132:135], v[188:191], v[20:23]
	v_mfma_f32_16x16x32_f16 v[24:27], v[136:139], v[188:191], v[24:27]
	v_mfma_f32_16x16x32_f16 v[28:31], v[140:143], v[188:191], v[28:31]
	v_mfma_f32_16x16x32_f16 v[32:35], v[144:147], v[188:191], v[32:35]
	v_mfma_f32_16x16x32_f16 v[36:39], v[132:135], v[192:195], v[36:39]
	v_mfma_f32_16x16x32_f16 v[40:43], v[136:139], v[192:195], v[40:43]
	v_mfma_f32_16x16x32_f16 v[44:47], v[140:143], v[192:195], v[44:47]
	v_mfma_f32_16x16x32_f16 v[48:51], v[144:147], v[192:195], v[48:51]
	v_mfma_f32_16x16x32_f16 v[52:55], v[132:135], v[196:199], v[52:55]
	v_mfma_f32_16x16x32_f16 v[56:59], v[136:139], v[196:199], v[56:59]
	v_mfma_f32_16x16x32_f16 v[60:63], v[140:143], v[196:199], v[60:63]
	v_mfma_f32_16x16x32_f16 v[64:67], v[144:147], v[196:199], v[64:67]
	s_waitcnt vmcnt(0) lgkmcnt(0)
	s_barrier
	s_add_i32 s53, s37, 0x8000
	s_cmp_lg_u32 s37, 0x18000
	s_cselect_b32 s53, s53, 0
	v_add_u32_e32 v168, s53, v165
	v_add_u32_e32 v169, s53, v164
	v_mfma_f32_16x16x32_f16 v[68:71], v[132:135], v[238:241], v[68:71]
	ds_read_b128 v[148:151], v168 offset:16
	ds_read_b128 v[184:187], v169 offset:16
	v_mfma_f32_16x16x32_f16 v[72:75], v[136:139], v[238:241], v[72:75]
	ds_read_b128 v[152:155], v168 offset:1040
	ds_read_b128 v[188:191], v169 offset:1040
	v_mfma_f32_16x16x32_f16 v[76:79], v[140:143], v[238:241], v[76:79]
	ds_read_b128 v[156:159], v168 offset:2064
	ds_read_b128 v[192:195], v169 offset:2064
	v_mfma_f32_16x16x32_f16 v[80:83], v[144:147], v[238:241], v[80:83]
	ds_read_b128 v[160:163], v168 offset:3088
	ds_read_b128 v[196:199], v169 offset:3088
	v_mfma_f32_16x16x32_f16 v[84:87], v[132:135], v[242:245], v[84:87]
	v_mfma_f32_16x16x32_f16 v[88:91], v[136:139], v[242:245], v[88:91]
	v_mfma_f32_16x16x32_f16 v[92:95], v[140:143], v[242:245], v[92:95]
	v_mfma_f32_16x16x32_f16 v[96:99], v[144:147], v[242:245], v[96:99]
	v_mfma_f32_16x16x32_f16 v[100:103], v[132:135], v[246:249], v[100:103]
	v_mfma_f32_16x16x32_f16 v[104:107], v[136:139], v[246:249], v[104:107]
	v_mfma_f32_16x16x32_f16 v[108:111], v[140:143], v[246:249], v[108:111]
	v_mfma_f32_16x16x32_f16 v[112:115], v[144:147], v[246:249], v[112:115]
	v_mfma_f32_16x16x32_f16 v[116:119], v[132:135], v[250:253], v[116:119]
	v_mfma_f32_16x16x32_f16 v[120:123], v[136:139], v[250:253], v[120:123]
	v_mfma_f32_16x16x32_f16 v[124:127], v[140:143], v[250:253], v[124:127]
	v_mfma_f32_16x16x32_f16 v[128:131], v[144:147], v[250:253], v[128:131]
	s_waitcnt lgkmcnt(0)
	s_mov_b32 s37, s53
	v_add_u32_e32 v169, s37, v164
	v_mfma_f32_16x16x32_f16 v[4:7], v[148:151], v[184:187], v[4:7]
	ds_read_b128 v[238:241], v169 offset:4112
	v_mfma_f32_16x16x32_f16 v[8:11], v[152:155], v[184:187], v[8:11]
	ds_read_b128 v[242:245], v169 offset:5136
	v_mfma_f32_16x16x32_f16 v[12:15], v[156:159], v[184:187], v[12:15]
	ds_read_b128 v[246:249], v169 offset:6160
	v_mfma_f32_16x16x32_f16 v[16:19], v[160:163], v[184:187], v[16:19]
	ds_read_b128 v[250:253], v169 offset:7184
	v_mfma_f32_16x16x32_f16 v[20:23], v[148:151], v[188:191], v[20:23]
	v_mfma_f32_16x16x32_f16 v[24:27], v[152:155], v[188:191], v[24:27]
	v_mfma_f32_16x16x32_f16 v[28:31], v[156:159], v[188:191], v[28:31]
	v_mfma_f32_16x16x32_f16 v[32:35], v[160:163], v[188:191], v[32:35]
	v_mfma_f32_16x16x32_f16 v[36:39], v[148:151], v[192:195], v[36:39]
	v_mfma_f32_16x16x32_f16 v[40:43], v[152:155], v[192:195], v[40:43]
	v_mfma_f32_16x16x32_f16 v[44:47], v[156:159], v[192:195], v[44:47]
	v_mfma_f32_16x16x32_f16 v[48:51], v[160:163], v[192:195], v[48:51]
	v_mfma_f32_16x16x32_f16 v[52:55], v[148:151], v[196:199], v[52:55]
	v_mfma_f32_16x16x32_f16 v[56:59], v[152:155], v[196:199], v[56:59]
	v_mfma_f32_16x16x32_f16 v[60:63], v[156:159], v[196:199], v[60:63]
	v_mfma_f32_16x16x32_f16 v[64:67], v[160:163], v[196:199], v[64:67]
	s_waitcnt lgkmcnt(0)
	s_barrier
	v_mfma_f32_16x16x32_f16 v[68:71], v[148:151], v[238:241], v[68:71]
	v_mfma_f32_16x16x32_f16 v[72:75], v[152:155], v[238:241], v[72:75]
	v_mfma_f32_16x16x32_f16 v[76:79], v[156:159], v[238:241], v[76:79]
	v_mfma_f32_16x16x32_f16 v[80:83], v[160:163], v[238:241], v[80:83]
	v_mfma_f32_16x16x32_f16 v[84:87], v[148:151], v[242:245], v[84:87]
	v_mfma_f32_16x16x32_f16 v[88:91], v[152:155], v[242:245], v[88:91]
	v_mfma_f32_16x16x32_f16 v[92:95], v[156:159], v[242:245], v[92:95]
	v_mfma_f32_16x16x32_f16 v[96:99], v[160:163], v[242:245], v[96:99]
	v_mfma_f32_16x16x32_f16 v[100:103], v[148:151], v[246:249], v[100:103]
	v_mfma_f32_16x16x32_f16 v[104:107], v[152:155], v[246:249], v[104:107]
	v_mfma_f32_16x16x32_f16 v[108:111], v[156:159], v[246:249], v[108:111]
	v_mfma_f32_16x16x32_f16 v[112:115], v[160:163], v[246:249], v[112:115]
	v_mfma_f32_16x16x32_f16 v[116:119], v[148:151], v[250:253], v[116:119]
	v_mfma_f32_16x16x32_f16 v[120:123], v[152:155], v[250:253], v[120:123]
	v_mfma_f32_16x16x32_f16 v[124:127], v[156:159], v[250:253], v[124:127]
	v_mfma_f32_16x16x32_f16 v[128:131], v[160:163], v[250:253], v[128:131]
	s_lshl_b64 s[80:81], s[28:29], 13
	s_add_u32 s80, s80, s34
	s_addc_u32 s81, s81, s35
	s_lshl_b32 s82, s65, 1
	s_add_u32 s80, s80, s82
	s_addc_u32 s81, s81, 0
	v_and_b32_e32 v172, 15, v200
	v_bfe_u32 v173, v200, 4, 2
	v_bfe_u32 v174, v200, 6, 2
	v_bfe_u32 v175, v200, 8, 1
	v_lshl_or_b32 v175, v175, 7, v172
	v_lshlrev_b32_e32 v175, 13, v175
	v_lshlrev_b32_e32 v174, 6, v174
	v_lshl_or_b32 v174, v173, 2, v174
	v_lshl_add_u32 v177, v174, 1, v175
	v_and_b32_e32 v172, 1, v173
	v_mul_u32_u24_e32 v172, 24, v172
	v_add_u32_e32 v177, v177, v172
	v_max_f32_e32 v4, 0, v4
	v_max_f32_e32 v5, 0, v5
	v_max_f32_e32 v6, 0, v6
	v_max_f32_e32 v7, 0, v7
	v_pk_mul_f32 v[4:5], v[4:5], v[4:5]
	v_pk_mul_f32 v[6:7], v[6:7], v[6:7]
	v_cvt_pk_f16_f32 v172, v4, v5
	v_cvt_pk_f16_f32 v173, v6, v7
	v_max_f32_e32 v8, 0, v8
	v_max_f32_e32 v9, 0, v9
	v_max_f32_e32 v10, 0, v10
	v_max_f32_e32 v11, 0, v11
	v_pk_mul_f32 v[8:9], v[8:9], v[8:9]
	v_pk_mul_f32 v[10:11], v[10:11], v[10:11]
	v_cvt_pk_f16_f32 v174, v8, v9
	v_cvt_pk_f16_f32 v175, v10, v11
	s_nop 1
	v_permlane16_swap_b32_e32 v172, v174
	v_permlane16_swap_b32_e32 v173, v175
	global_store_dwordx4 v177, v[172:175], s[80:81]
	v_max_f32_e32 v12, 0, v12
	v_max_f32_e32 v13, 0, v13
	v_max_f32_e32 v14, 0, v14
	v_max_f32_e32 v15, 0, v15
	v_pk_mul_f32 v[12:13], v[12:13], v[12:13]
	v_pk_mul_f32 v[14:15], v[14:15], v[14:15]
	v_cvt_pk_f16_f32 v228, v12, v13
	v_cvt_pk_f16_f32 v229, v14, v15
	v_max_f32_e32 v16, 0, v16
	v_max_f32_e32 v17, 0, v17
	v_max_f32_e32 v18, 0, v18
	v_max_f32_e32 v19, 0, v19
	v_pk_mul_f32 v[16:17], v[16:17], v[16:17]
	v_pk_mul_f32 v[18:19], v[18:19], v[18:19]
	v_cvt_pk_f16_f32 v230, v16, v17
	v_cvt_pk_f16_f32 v231, v18, v19
	s_nop 1
	v_permlane16_swap_b32_e32 v228, v230
	v_permlane16_swap_b32_e32 v229, v231
	global_store_dwordx4 v177, v[228:231], s[80:81] offset:64
	v_add_u32_e32 v177, 0x20000, v177
	v_max_f32_e32 v20, 0, v20
	v_max_f32_e32 v21, 0, v21
	v_max_f32_e32 v22, 0, v22
	v_max_f32_e32 v23, 0, v23
	v_pk_mul_f32 v[20:21], v[20:21], v[20:21]
	v_pk_mul_f32 v[22:23], v[22:23], v[22:23]
	v_cvt_pk_f16_f32 v172, v20, v21
	v_cvt_pk_f16_f32 v173, v22, v23
	v_max_f32_e32 v24, 0, v24
	v_max_f32_e32 v25, 0, v25
	v_max_f32_e32 v26, 0, v26
	v_max_f32_e32 v27, 0, v27
	v_pk_mul_f32 v[24:25], v[24:25], v[24:25]
	v_pk_mul_f32 v[26:27], v[26:27], v[26:27]
	v_cvt_pk_f16_f32 v174, v24, v25
	v_cvt_pk_f16_f32 v175, v26, v27
	s_nop 1
	v_permlane16_swap_b32_e32 v172, v174
	v_permlane16_swap_b32_e32 v173, v175
	global_store_dwordx4 v177, v[172:175], s[80:81]
	v_max_f32_e32 v28, 0, v28
	v_max_f32_e32 v29, 0, v29
	v_max_f32_e32 v30, 0, v30
	v_max_f32_e32 v31, 0, v31
	v_pk_mul_f32 v[28:29], v[28:29], v[28:29]
	v_pk_mul_f32 v[30:31], v[30:31], v[30:31]
	v_cvt_pk_f16_f32 v228, v28, v29
	v_cvt_pk_f16_f32 v229, v30, v31
	v_max_f32_e32 v32, 0, v32
	v_max_f32_e32 v33, 0, v33
	v_max_f32_e32 v34, 0, v34
	v_max_f32_e32 v35, 0, v35
	v_pk_mul_f32 v[32:33], v[32:33], v[32:33]
	v_pk_mul_f32 v[34:35], v[34:35], v[34:35]
	v_cvt_pk_f16_f32 v230, v32, v33
	v_cvt_pk_f16_f32 v231, v34, v35
	s_nop 1
	v_permlane16_swap_b32_e32 v228, v230
	v_permlane16_swap_b32_e32 v229, v231
	global_store_dwordx4 v177, v[228:231], s[80:81] offset:64
	v_add_u32_e32 v177, 0x20000, v177
	v_max_f32_e32 v36, 0, v36
	v_max_f32_e32 v37, 0, v37
	v_max_f32_e32 v38, 0, v38
	v_max_f32_e32 v39, 0, v39
	v_pk_mul_f32 v[36:37], v[36:37], v[36:37]
	v_pk_mul_f32 v[38:39], v[38:39], v[38:39]
	v_cvt_pk_f16_f32 v172, v36, v37
	v_cvt_pk_f16_f32 v173, v38, v39
	v_max_f32_e32 v40, 0, v40
	v_max_f32_e32 v41, 0, v41
	v_max_f32_e32 v42, 0, v42
	v_max_f32_e32 v43, 0, v43
	v_pk_mul_f32 v[40:41], v[40:41], v[40:41]
	v_pk_mul_f32 v[42:43], v[42:43], v[42:43]
	v_cvt_pk_f16_f32 v174, v40, v41
	v_cvt_pk_f16_f32 v175, v42, v43
	s_nop 1
	v_permlane16_swap_b32_e32 v172, v174
	v_permlane16_swap_b32_e32 v173, v175
	global_store_dwordx4 v177, v[172:175], s[80:81]
	v_max_f32_e32 v44, 0, v44
	v_max_f32_e32 v45, 0, v45
	v_max_f32_e32 v46, 0, v46
	v_max_f32_e32 v47, 0, v47
	v_pk_mul_f32 v[44:45], v[44:45], v[44:45]
	v_pk_mul_f32 v[46:47], v[46:47], v[46:47]
	v_cvt_pk_f16_f32 v228, v44, v45
	v_cvt_pk_f16_f32 v229, v46, v47
	v_max_f32_e32 v48, 0, v48
	v_max_f32_e32 v49, 0, v49
	v_max_f32_e32 v50, 0, v50
	v_max_f32_e32 v51, 0, v51
	v_pk_mul_f32 v[48:49], v[48:49], v[48:49]
	v_pk_mul_f32 v[50:51], v[50:51], v[50:51]
	v_cvt_pk_f16_f32 v230, v48, v49
	v_cvt_pk_f16_f32 v231, v50, v51
	s_nop 1
	v_permlane16_swap_b32_e32 v228, v230
	v_permlane16_swap_b32_e32 v229, v231
	global_store_dwordx4 v177, v[228:231], s[80:81] offset:64
	v_add_u32_e32 v177, 0x20000, v177
	v_max_f32_e32 v52, 0, v52
	v_max_f32_e32 v53, 0, v53
	v_max_f32_e32 v54, 0, v54
	v_max_f32_e32 v55, 0, v55
	v_pk_mul_f32 v[52:53], v[52:53], v[52:53]
	v_pk_mul_f32 v[54:55], v[54:55], v[54:55]
	v_cvt_pk_f16_f32 v172, v52, v53
	v_cvt_pk_f16_f32 v173, v54, v55
	v_max_f32_e32 v56, 0, v56
	v_max_f32_e32 v57, 0, v57
	v_max_f32_e32 v58, 0, v58
	v_max_f32_e32 v59, 0, v59
	v_pk_mul_f32 v[56:57], v[56:57], v[56:57]
	v_pk_mul_f32 v[58:59], v[58:59], v[58:59]
	v_cvt_pk_f16_f32 v174, v56, v57
	v_cvt_pk_f16_f32 v175, v58, v59
	s_nop 1
	v_permlane16_swap_b32_e32 v172, v174
	v_permlane16_swap_b32_e32 v173, v175
	global_store_dwordx4 v177, v[172:175], s[80:81]
	v_max_f32_e32 v60, 0, v60
	v_max_f32_e32 v61, 0, v61
	v_max_f32_e32 v62, 0, v62
	v_max_f32_e32 v63, 0, v63
	v_pk_mul_f32 v[60:61], v[60:61], v[60:61]
	v_pk_mul_f32 v[62:63], v[62:63], v[62:63]
	v_cvt_pk_f16_f32 v228, v60, v61
	v_cvt_pk_f16_f32 v229, v62, v63
	v_max_f32_e32 v64, 0, v64
	v_max_f32_e32 v65, 0, v65
	v_max_f32_e32 v66, 0, v66
	v_max_f32_e32 v67, 0, v67
	v_pk_mul_f32 v[64:65], v[64:65], v[64:65]
	v_pk_mul_f32 v[66:67], v[66:67], v[66:67]
	v_cvt_pk_f16_f32 v230, v64, v65
	v_cvt_pk_f16_f32 v231, v66, v67
	s_nop 1
	v_permlane16_swap_b32_e32 v228, v230
	v_permlane16_swap_b32_e32 v229, v231
	global_store_dwordx4 v177, v[228:231], s[80:81] offset:64
	v_add_u32_e32 v177, 0x20000, v177
	v_max_f32_e32 v68, 0, v68
	v_max_f32_e32 v69, 0, v69
	v_max_f32_e32 v70, 0, v70
	v_max_f32_e32 v71, 0, v71
	v_pk_mul_f32 v[68:69], v[68:69], v[68:69]
	v_pk_mul_f32 v[70:71], v[70:71], v[70:71]
	v_cvt_pk_f16_f32 v172, v68, v69
	v_cvt_pk_f16_f32 v173, v70, v71
	v_max_f32_e32 v72, 0, v72
	v_max_f32_e32 v73, 0, v73
	v_max_f32_e32 v74, 0, v74
	v_max_f32_e32 v75, 0, v75
	v_pk_mul_f32 v[72:73], v[72:73], v[72:73]
	v_pk_mul_f32 v[74:75], v[74:75], v[74:75]
	v_cvt_pk_f16_f32 v174, v72, v73
	v_cvt_pk_f16_f32 v175, v74, v75
	s_nop 1
	v_permlane16_swap_b32_e32 v172, v174
	v_permlane16_swap_b32_e32 v173, v175
	global_store_dwordx4 v177, v[172:175], s[80:81]
	v_max_f32_e32 v76, 0, v76
	v_max_f32_e32 v77, 0, v77
	v_max_f32_e32 v78, 0, v78
	v_max_f32_e32 v79, 0, v79
	v_pk_mul_f32 v[76:77], v[76:77], v[76:77]
	v_pk_mul_f32 v[78:79], v[78:79], v[78:79]
	v_cvt_pk_f16_f32 v228, v76, v77
	v_cvt_pk_f16_f32 v229, v78, v79
	v_max_f32_e32 v80, 0, v80
	v_max_f32_e32 v81, 0, v81
	v_max_f32_e32 v82, 0, v82
	v_max_f32_e32 v83, 0, v83
	v_pk_mul_f32 v[80:81], v[80:81], v[80:81]
	v_pk_mul_f32 v[82:83], v[82:83], v[82:83]
	v_cvt_pk_f16_f32 v230, v80, v81
	v_cvt_pk_f16_f32 v231, v82, v83
	s_nop 1
	v_permlane16_swap_b32_e32 v228, v230
	v_permlane16_swap_b32_e32 v229, v231
	global_store_dwordx4 v177, v[228:231], s[80:81] offset:64
	v_add_u32_e32 v177, 0x20000, v177
	v_max_f32_e32 v84, 0, v84
	v_max_f32_e32 v85, 0, v85
	v_max_f32_e32 v86, 0, v86
	v_max_f32_e32 v87, 0, v87
	v_pk_mul_f32 v[84:85], v[84:85], v[84:85]
	v_pk_mul_f32 v[86:87], v[86:87], v[86:87]
	v_cvt_pk_f16_f32 v172, v84, v85
	v_cvt_pk_f16_f32 v173, v86, v87
	v_max_f32_e32 v88, 0, v88
	v_max_f32_e32 v89, 0, v89
	v_max_f32_e32 v90, 0, v90
	v_max_f32_e32 v91, 0, v91
	v_pk_mul_f32 v[88:89], v[88:89], v[88:89]
	v_pk_mul_f32 v[90:91], v[90:91], v[90:91]
	v_cvt_pk_f16_f32 v174, v88, v89
	v_cvt_pk_f16_f32 v175, v90, v91
	s_nop 1
	v_permlane16_swap_b32_e32 v172, v174
	v_permlane16_swap_b32_e32 v173, v175
	global_store_dwordx4 v177, v[172:175], s[80:81]
	v_max_f32_e32 v92, 0, v92
	v_max_f32_e32 v93, 0, v93
	v_max_f32_e32 v94, 0, v94
	v_max_f32_e32 v95, 0, v95
	v_pk_mul_f32 v[92:93], v[92:93], v[92:93]
	v_pk_mul_f32 v[94:95], v[94:95], v[94:95]
	v_cvt_pk_f16_f32 v228, v92, v93
	v_cvt_pk_f16_f32 v229, v94, v95
	v_max_f32_e32 v96, 0, v96
	v_max_f32_e32 v97, 0, v97
	v_max_f32_e32 v98, 0, v98
	v_max_f32_e32 v99, 0, v99
	v_pk_mul_f32 v[96:97], v[96:97], v[96:97]
	v_pk_mul_f32 v[98:99], v[98:99], v[98:99]
	v_cvt_pk_f16_f32 v230, v96, v97
	v_cvt_pk_f16_f32 v231, v98, v99
	s_nop 1
	v_permlane16_swap_b32_e32 v228, v230
	v_permlane16_swap_b32_e32 v229, v231
	global_store_dwordx4 v177, v[228:231], s[80:81] offset:64
	v_add_u32_e32 v177, 0x20000, v177
	v_max_f32_e32 v100, 0, v100
	v_max_f32_e32 v101, 0, v101
	v_max_f32_e32 v102, 0, v102
	v_max_f32_e32 v103, 0, v103
	v_pk_mul_f32 v[100:101], v[100:101], v[100:101]
	v_pk_mul_f32 v[102:103], v[102:103], v[102:103]
	v_cvt_pk_f16_f32 v172, v100, v101
	v_cvt_pk_f16_f32 v173, v102, v103
	v_max_f32_e32 v104, 0, v104
	v_max_f32_e32 v105, 0, v105
	v_max_f32_e32 v106, 0, v106
	v_max_f32_e32 v107, 0, v107
	v_pk_mul_f32 v[104:105], v[104:105], v[104:105]
	v_pk_mul_f32 v[106:107], v[106:107], v[106:107]
	v_cvt_pk_f16_f32 v174, v104, v105
	v_cvt_pk_f16_f32 v175, v106, v107
	s_nop 1
	v_permlane16_swap_b32_e32 v172, v174
	v_permlane16_swap_b32_e32 v173, v175
	global_store_dwordx4 v177, v[172:175], s[80:81]
	v_max_f32_e32 v108, 0, v108
	v_max_f32_e32 v109, 0, v109
	v_max_f32_e32 v110, 0, v110
	v_max_f32_e32 v111, 0, v111
	v_pk_mul_f32 v[108:109], v[108:109], v[108:109]
	v_pk_mul_f32 v[110:111], v[110:111], v[110:111]
	v_cvt_pk_f16_f32 v228, v108, v109
	v_cvt_pk_f16_f32 v229, v110, v111
	v_max_f32_e32 v112, 0, v112
	v_max_f32_e32 v113, 0, v113
	v_max_f32_e32 v114, 0, v114
	v_max_f32_e32 v115, 0, v115
	v_pk_mul_f32 v[112:113], v[112:113], v[112:113]
	v_pk_mul_f32 v[114:115], v[114:115], v[114:115]
	v_cvt_pk_f16_f32 v230, v112, v113
	v_cvt_pk_f16_f32 v231, v114, v115
	s_nop 1
	v_permlane16_swap_b32_e32 v228, v230
	v_permlane16_swap_b32_e32 v229, v231
	global_store_dwordx4 v177, v[228:231], s[80:81] offset:64
	v_add_u32_e32 v177, 0x20000, v177
	v_max_f32_e32 v116, 0, v116
	v_max_f32_e32 v117, 0, v117
	v_max_f32_e32 v118, 0, v118
	v_max_f32_e32 v119, 0, v119
	v_pk_mul_f32 v[116:117], v[116:117], v[116:117]
	v_pk_mul_f32 v[118:119], v[118:119], v[118:119]
	v_cvt_pk_f16_f32 v172, v116, v117
	v_cvt_pk_f16_f32 v173, v118, v119
	v_max_f32_e32 v120, 0, v120
	v_max_f32_e32 v121, 0, v121
	v_max_f32_e32 v122, 0, v122
	v_max_f32_e32 v123, 0, v123
	v_pk_mul_f32 v[120:121], v[120:121], v[120:121]
	v_pk_mul_f32 v[122:123], v[122:123], v[122:123]
	v_cvt_pk_f16_f32 v174, v120, v121
	v_cvt_pk_f16_f32 v175, v122, v123
	s_nop 1
	v_permlane16_swap_b32_e32 v172, v174
	v_permlane16_swap_b32_e32 v173, v175
	global_store_dwordx4 v177, v[172:175], s[80:81]
	v_max_f32_e32 v124, 0, v124
	v_max_f32_e32 v125, 0, v125
	v_max_f32_e32 v126, 0, v126
	v_max_f32_e32 v127, 0, v127
	v_pk_mul_f32 v[124:125], v[124:125], v[124:125]
	v_pk_mul_f32 v[126:127], v[126:127], v[126:127]
	v_cvt_pk_f16_f32 v228, v124, v125
	v_cvt_pk_f16_f32 v229, v126, v127
	v_max_f32_e32 v128, 0, v128
	v_max_f32_e32 v129, 0, v129
	v_max_f32_e32 v130, 0, v130
	v_max_f32_e32 v131, 0, v131
	v_pk_mul_f32 v[128:129], v[128:129], v[128:129]
	v_pk_mul_f32 v[130:131], v[130:131], v[130:131]
	v_cvt_pk_f16_f32 v230, v128, v129
	v_cvt_pk_f16_f32 v231, v130, v131
	s_nop 1
	v_permlane16_swap_b32_e32 v228, v230
	v_permlane16_swap_b32_e32 v229, v231
	global_store_dwordx4 v177, v[228:231], s[80:81] offset:64
	s_nop 1
	s_add_i32 s54, s54, s76
	s_cmp_ge_i32 s54, s58
	s_cbranch_scc1 .LBB0_780
	s_branch .LBB0_725

.Lt_gin:
	v_add_u32_e32 v169, s47, v164
	v_mfma_f32_16x16x32_f16 v[4:7], v[132:135], v[184:187], v[4:7]
	ds_read_b128 v[238:241], v169 offset:4112
	v_mfma_f32_16x16x32_f16 v[8:11], v[136:139], v[184:187], v[8:11]
	ds_read_b128 v[242:245], v169 offset:5136
	v_mfma_f32_16x16x32_f16 v[12:15], v[140:143], v[184:187], v[12:15]
	ds_read_b128 v[246:249], v169 offset:6160
	v_mfma_f32_16x16x32_f16 v[16:19], v[144:147], v[184:187], v[16:19]
	ds_read_b128 v[250:253], v169 offset:7184
	v_mfma_f32_16x16x32_f16 v[20:23], v[132:135], v[188:191], v[20:23]
	v_mfma_f32_16x16x32_f16 v[24:27], v[136:139], v[188:191], v[24:27]
	v_mfma_f32_16x16x32_f16 v[28:31], v[140:143], v[188:191], v[28:31]
	v_mfma_f32_16x16x32_f16 v[32:35], v[144:147], v[188:191], v[32:35]
	v_mfma_f32_16x16x32_f16 v[36:39], v[132:135], v[192:195], v[36:39]
	v_mfma_f32_16x16x32_f16 v[40:43], v[136:139], v[192:195], v[40:43]
	v_mfma_f32_16x16x32_f16 v[44:47], v[140:143], v[192:195], v[44:47]
	v_mfma_f32_16x16x32_f16 v[48:51], v[144:147], v[192:195], v[48:51]
	v_mfma_f32_16x16x32_f16 v[52:55], v[132:135], v[196:199], v[52:55]
	v_mfma_f32_16x16x32_f16 v[56:59], v[136:139], v[196:199], v[56:59]
	v_mfma_f32_16x16x32_f16 v[60:63], v[140:143], v[196:199], v[60:63]
	v_mfma_f32_16x16x32_f16 v[64:67], v[144:147], v[196:199], v[64:67]
	s_waitcnt vmcnt(8) lgkmcnt(0)
	s_barrier
	s_add_i32 s48, s47, 0x8000
	s_cmp_lg_u32 s47, 0x18000
	s_cselect_b32 s48, s48, 0
	v_add_u32_e32 v168, s48, v165
	v_add_u32_e32 v169, s48, v164
	s_add_u32 vcc_lo, s32, s47
	v_mfma_f32_16x16x32_f16 v[68:71], v[132:135], v[238:241], v[68:71]
	ds_read_b128 v[148:151], v168 offset:16
	ds_read_b128 v[184:187], v169 offset:16
	v_mfma_f32_16x16x32_f16 v[72:75], v[136:139], v[238:241], v[72:75]
	ds_read_b128 v[152:155], v168 offset:1040
	ds_read_b128 v[188:191], v169 offset:1040
	v_mfma_f32_16x16x32_f16 v[76:79], v[140:143], v[238:241], v[76:79]
	ds_read_b128 v[156:159], v168 offset:2064
	ds_read_b128 v[192:195], v169 offset:2064
	v_mfma_f32_16x16x32_f16 v[80:83], v[144:147], v[238:241], v[80:83]
	ds_read_b128 v[160:163], v168 offset:3088
	ds_read_b128 v[196:199], v169 offset:3088
	v_mfma_f32_16x16x32_f16 v[84:87], v[132:135], v[242:245], v[84:87]
	v_mfma_f32_16x16x32_f16 v[88:91], v[136:139], v[242:245], v[88:91]
	v_mfma_f32_16x16x32_f16 v[92:95], v[140:143], v[242:245], v[92:95]
	v_mfma_f32_16x16x32_f16 v[96:99], v[144:147], v[242:245], v[96:99]
	v_mfma_f32_16x16x32_f16 v[100:103], v[132:135], v[246:249], v[100:103]
	s_mov_b32 m0, vcc_lo
	s_nop 0
	global_load_lds_dwordx4 v170, s[36:37]
	v_mfma_f32_16x16x32_f16 v[104:107], v[136:139], v[246:249], v[104:107]
	s_add_u32 m0, vcc_lo, 0x400
	s_nop 0
	global_load_lds_dwordx4 v171, s[36:37]
	v_mfma_f32_16x16x32_f16 v[108:111], v[140:143], v[246:249], v[108:111]
	s_add_u32 m0, vcc_lo, 0x4000
	s_nop 0
	global_load_lds_dwordx4 v170, s[42:43]
	v_mfma_f32_16x16x32_f16 v[112:115], v[144:147], v[246:249], v[112:115]
	s_add_u32 m0, vcc_lo, 0x4400
	s_nop 0
	global_load_lds_dwordx4 v171, s[42:43]
	v_mfma_f32_16x16x32_f16 v[116:119], v[132:135], v[250:253], v[116:119]
	v_mfma_f32_16x16x32_f16 v[120:123], v[136:139], v[250:253], v[120:123]
	v_mfma_f32_16x16x32_f16 v[124:127], v[140:143], v[250:253], v[124:127]
	v_mfma_f32_16x16x32_f16 v[128:131], v[144:147], v[250:253], v[128:131]
	s_waitcnt lgkmcnt(0)
	s_mov_b32 s47, s48
	s_add_u32 s36, s36, 64
	s_addc_u32 s37, s37, 0
	s_add_u32 s42, s42, 64
	s_addc_u32 s43, s43, 0
	v_add_u32_e32 v169, s47, v164
	v_mfma_f32_16x16x32_f16 v[4:7], v[148:151], v[184:187], v[4:7]
	ds_read_b128 v[238:241], v169 offset:4112
	v_mfma_f32_16x16x32_f16 v[8:11], v[152:155], v[184:187], v[8:11]
	ds_read_b128 v[242:245], v169 offset:5136
	v_mfma_f32_16x16x32_f16 v[12:15], v[156:159], v[184:187], v[12:15]
	ds_read_b128 v[246:249], v169 offset:6160
	v_mfma_f32_16x16x32_f16 v[16:19], v[160:163], v[184:187], v[16:19]
	ds_read_b128 v[250:253], v169 offset:7184
	v_mfma_f32_16x16x32_f16 v[20:23], v[148:151], v[188:191], v[20:23]
	v_mfma_f32_16x16x32_f16 v[24:27], v[152:155], v[188:191], v[24:27]
	v_mfma_f32_16x16x32_f16 v[28:31], v[156:159], v[188:191], v[28:31]
	v_mfma_f32_16x16x32_f16 v[32:35], v[160:163], v[188:191], v[32:35]
	v_mfma_f32_16x16x32_f16 v[36:39], v[148:151], v[192:195], v[36:39]
	v_mfma_f32_16x16x32_f16 v[40:43], v[152:155], v[192:195], v[40:43]
	v_mfma_f32_16x16x32_f16 v[44:47], v[156:159], v[192:195], v[44:47]
	v_mfma_f32_16x16x32_f16 v[48:51], v[160:163], v[192:195], v[48:51]
	v_mfma_f32_16x16x32_f16 v[52:55], v[148:151], v[196:199], v[52:55]
	v_mfma_f32_16x16x32_f16 v[56:59], v[152:155], v[196:199], v[56:59]
	v_mfma_f32_16x16x32_f16 v[60:63], v[156:159], v[196:199], v[60:63]
	v_mfma_f32_16x16x32_f16 v[64:67], v[160:163], v[196:199], v[64:67]
	s_waitcnt vmcnt(8) lgkmcnt(0)
	s_barrier
	s_add_i32 s48, s47, 0x8000
	s_cmp_lg_u32 s47, 0x18000
	s_cselect_b32 s48, s48, 0
	v_add_u32_e32 v168, s48, v165
	v_add_u32_e32 v169, s48, v164
	s_add_u32 vcc_lo, s32, s47
	v_mfma_f32_16x16x32_f16 v[68:71], v[148:151], v[238:241], v[68:71]
	ds_read_b128 v[132:135], v168 offset:16
	ds_read_b128 v[184:187], v169 offset:16
	v_mfma_f32_16x16x32_f16 v[72:75], v[152:155], v[238:241], v[72:75]
	ds_read_b128 v[136:139], v168 offset:1040
	ds_read_b128 v[188:191], v169 offset:1040
	v_mfma_f32_16x16x32_f16 v[76:79], v[156:159], v[238:241], v[76:79]
	ds_read_b128 v[140:143], v168 offset:2064
	ds_read_b128 v[192:195], v169 offset:2064
	v_mfma_f32_16x16x32_f16 v[80:83], v[160:163], v[238:241], v[80:83]
	ds_read_b128 v[144:147], v168 offset:3088
	ds_read_b128 v[196:199], v169 offset:3088
	v_mfma_f32_16x16x32_f16 v[84:87], v[148:151], v[242:245], v[84:87]
	v_mfma_f32_16x16x32_f16 v[88:91], v[152:155], v[242:245], v[88:91]
	v_mfma_f32_16x16x32_f16 v[92:95], v[156:159], v[242:245], v[92:95]
	v_mfma_f32_16x16x32_f16 v[96:99], v[160:163], v[242:245], v[96:99]
	v_mfma_f32_16x16x32_f16 v[100:103], v[148:151], v[246:249], v[100:103]
	s_mov_b32 m0, vcc_lo
	s_nop 0
	global_load_lds_dwordx4 v170, s[36:37]
	v_mfma_f32_16x16x32_f16 v[104:107], v[152:155], v[246:249], v[104:107]
	s_add_u32 m0, vcc_lo, 0x400
	s_nop 0
	global_load_lds_dwordx4 v171, s[36:37]
	v_mfma_f32_16x16x32_f16 v[108:111], v[156:159], v[246:249], v[108:111]
	s_add_u32 m0, vcc_lo, 0x4000
	s_nop 0
	global_load_lds_dwordx4 v170, s[42:43]
	v_mfma_f32_16x16x32_f16 v[112:115], v[160:163], v[246:249], v[112:115]
	s_add_u32 m0, vcc_lo, 0x4400
	s_nop 0
	global_load_lds_dwordx4 v171, s[42:43]
	v_mfma_f32_16x16x32_f16 v[116:119], v[148:151], v[250:253], v[116:119]
	v_mfma_f32_16x16x32_f16 v[120:123], v[152:155], v[250:253], v[120:123]
	v_mfma_f32_16x16x32_f16 v[124:127], v[156:159], v[250:253], v[124:127]
	v_mfma_f32_16x16x32_f16 v[128:131], v[160:163], v[250:253], v[128:131]
	s_waitcnt lgkmcnt(0)
	s_mov_b32 s47, s48
	s_add_u32 s36, s36, 64
	s_addc_u32 s37, s37, 0
	s_add_u32 s42, s42, 64
	s_addc_u32 s43, s43, 0
	s_add_i32 s49, s49, 2
	s_cmp_lt_u32 s49, 28
	s_cbranch_scc1 .Lt_gin
	v_add_u32_e32 v169, s47, v164
	v_mfma_f32_16x16x32_f16 v[4:7], v[132:135], v[184:187], v[4:7]
	ds_read_b128 v[238:241], v169 offset:4112
	v_mfma_f32_16x16x32_f16 v[8:11], v[136:139], v[184:187], v[8:11]
	ds_read_b128 v[242:245], v169 offset:5136
	v_mfma_f32_16x16x32_f16 v[12:15], v[140:143], v[184:187], v[12:15]
	ds_read_b128 v[246:249], v169 offset:6160
	v_mfma_f32_16x16x32_f16 v[16:19], v[144:147], v[184:187], v[16:19]
	ds_read_b128 v[250:253], v169 offset:7184
	v_mfma_f32_16x16x32_f16 v[20:23], v[132:135], v[188:191], v[20:23]
	v_mfma_f32_16x16x32_f16 v[24:27], v[136:139], v[188:191], v[24:27]
	v_mfma_f32_16x16x32_f16 v[28:31], v[140:143], v[188:191], v[28:31]
	v_mfma_f32_16x16x32_f16 v[32:35], v[144:147], v[188:191], v[32:35]
	v_mfma_f32_16x16x32_f16 v[36:39], v[132:135], v[192:195], v[36:39]
	v_mfma_f32_16x16x32_f16 v[40:43], v[136:139], v[192:195], v[40:43]
	v_mfma_f32_16x16x32_f16 v[44:47], v[140:143], v[192:195], v[44:47]
	v_mfma_f32_16x16x32_f16 v[48:51], v[144:147], v[192:195], v[48:51]
	v_mfma_f32_16x16x32_f16 v[52:55], v[132:135], v[196:199], v[52:55]
	v_mfma_f32_16x16x32_f16 v[56:59], v[136:139], v[196:199], v[56:59]
	v_mfma_f32_16x16x32_f16 v[60:63], v[140:143], v[196:199], v[60:63]
	v_mfma_f32_16x16x32_f16 v[64:67], v[144:147], v[196:199], v[64:67]
	s_waitcnt vmcnt(8) lgkmcnt(0)
	s_barrier
	s_add_i32 s48, s47, 0x8000
	s_cmp_lg_u32 s47, 0x18000
	s_cselect_b32 s48, s48, 0
	v_add_u32_e32 v168, s48, v165
	v_add_u32_e32 v169, s48, v164
	v_mfma_f32_16x16x32_f16 v[68:71], v[132:135], v[238:241], v[68:71]
	ds_read_b128 v[148:151], v168 offset:16
	ds_read_b128 v[184:187], v169 offset:16
	v_mfma_f32_16x16x32_f16 v[72:75], v[136:139], v[238:241], v[72:75]
	ds_read_b128 v[152:155], v168 offset:1040
	ds_read_b128 v[188:191], v169 offset:1040
	v_mfma_f32_16x16x32_f16 v[76:79], v[140:143], v[238:241], v[76:79]
	ds_read_b128 v[156:159], v168 offset:2064
	ds_read_b128 v[192:195], v169 offset:2064
	v_mfma_f32_16x16x32_f16 v[80:83], v[144:147], v[238:241], v[80:83]
	ds_read_b128 v[160:163], v168 offset:3088
	ds_read_b128 v[196:199], v169 offset:3088
	v_mfma_f32_16x16x32_f16 v[84:87], v[132:135], v[242:245], v[84:87]
	v_mfma_f32_16x16x32_f16 v[88:91], v[136:139], v[242:245], v[88:91]
	v_mfma_f32_16x16x32_f16 v[92:95], v[140:143], v[242:245], v[92:95]
	v_mfma_f32_16x16x32_f16 v[96:99], v[144:147], v[242:245], v[96:99]
	v_mfma_f32_16x16x32_f16 v[100:103], v[132:135], v[246:249], v[100:103]
	v_mfma_f32_16x16x32_f16 v[104:107], v[136:139], v[246:249], v[104:107]
	v_mfma_f32_16x16x32_f16 v[108:111], v[140:143], v[246:249], v[108:111]
	v_mfma_f32_16x16x32_f16 v[112:115], v[144:147], v[246:249], v[112:115]
	v_mfma_f32_16x16x32_f16 v[116:119], v[132:135], v[250:253], v[116:119]
	v_mfma_f32_16x16x32_f16 v[120:123], v[136:139], v[250:253], v[120:123]
	v_mfma_f32_16x16x32_f16 v[124:127], v[140:143], v[250:253], v[124:127]
	v_mfma_f32_16x16x32_f16 v[128:131], v[144:147], v[250:253], v[128:131]
	s_waitcnt lgkmcnt(0)
	s_mov_b32 s47, s48
	v_add_u32_e32 v169, s47, v164
	v_mfma_f32_16x16x32_f16 v[4:7], v[148:151], v[184:187], v[4:7]
	ds_read_b128 v[238:241], v169 offset:4112
	v_mfma_f32_16x16x32_f16 v[8:11], v[152:155], v[184:187], v[8:11]
	ds_read_b128 v[242:245], v169 offset:5136
	v_mfma_f32_16x16x32_f16 v[12:15], v[156:159], v[184:187], v[12:15]
	ds_read_b128 v[246:249], v169 offset:6160
	v_mfma_f32_16x16x32_f16 v[16:19], v[160:163], v[184:187], v[16:19]
	ds_read_b128 v[250:253], v169 offset:7184
	v_mfma_f32_16x16x32_f16 v[20:23], v[148:151], v[188:191], v[20:23]
	v_mfma_f32_16x16x32_f16 v[24:27], v[152:155], v[188:191], v[24:27]
	v_mfma_f32_16x16x32_f16 v[28:31], v[156:159], v[188:191], v[28:31]
	v_mfma_f32_16x16x32_f16 v[32:35], v[160:163], v[188:191], v[32:35]
	v_mfma_f32_16x16x32_f16 v[36:39], v[148:151], v[192:195], v[36:39]
	v_mfma_f32_16x16x32_f16 v[40:43], v[152:155], v[192:195], v[40:43]
	v_mfma_f32_16x16x32_f16 v[44:47], v[156:159], v[192:195], v[44:47]
	v_mfma_f32_16x16x32_f16 v[48:51], v[160:163], v[192:195], v[48:51]
	v_mfma_f32_16x16x32_f16 v[52:55], v[148:151], v[196:199], v[52:55]
	v_mfma_f32_16x16x32_f16 v[56:59], v[152:155], v[196:199], v[56:59]
	v_mfma_f32_16x16x32_f16 v[60:63], v[156:159], v[196:199], v[60:63]
	v_mfma_f32_16x16x32_f16 v[64:67], v[160:163], v[196:199], v[64:67]
	s_waitcnt vmcnt(4) lgkmcnt(0)
	s_barrier
	s_add_i32 s48, s47, 0x8000
	s_cmp_lg_u32 s47, 0x18000
	s_cselect_b32 s48, s48, 0
	v_add_u32_e32 v168, s48, v165
	v_add_u32_e32 v169, s48, v164
	v_mfma_f32_16x16x32_f16 v[68:71], v[148:151], v[238:241], v[68:71]
	ds_read_b128 v[132:135], v168 offset:16
	ds_read_b128 v[184:187], v169 offset:16
	v_mfma_f32_16x16x32_f16 v[72:75], v[152:155], v[238:241], v[72:75]
	ds_read_b128 v[136:139], v168 offset:1040
	ds_read_b128 v[188:191], v169 offset:1040
	v_mfma_f32_16x16x32_f16 v[76:79], v[156:159], v[238:241], v[76:79]
	ds_read_b128 v[140:143], v168 offset:2064
	ds_read_b128 v[192:195], v169 offset:2064
	v_mfma_f32_16x16x32_f16 v[80:83], v[160:163], v[238:241], v[80:83]
	ds_read_b128 v[144:147], v168 offset:3088
	ds_read_b128 v[196:199], v169 offset:3088
	v_mfma_f32_16x16x32_f16 v[84:87], v[148:151], v[242:245], v[84:87]
	v_mfma_f32_16x16x32_f16 v[88:91], v[152:155], v[242:245], v[88:91]
	v_mfma_f32_16x16x32_f16 v[92:95], v[156:159], v[242:245], v[92:95]
	v_mfma_f32_16x16x32_f16 v[96:99], v[160:163], v[242:245], v[96:99]
	v_mfma_f32_16x16x32_f16 v[100:103], v[148:151], v[246:249], v[100:103]
	v_mfma_f32_16x16x32_f16 v[104:107], v[152:155], v[246:249], v[104:107]
	v_mfma_f32_16x16x32_f16 v[108:111], v[156:159], v[246:249], v[108:111]
	v_mfma_f32_16x16x32_f16 v[112:115], v[160:163], v[246:249], v[112:115]
	v_mfma_f32_16x16x32_f16 v[116:119], v[148:151], v[250:253], v[116:119]
	v_mfma_f32_16x16x32_f16 v[120:123], v[152:155], v[250:253], v[120:123]
	v_mfma_f32_16x16x32_f16 v[124:127], v[156:159], v[250:253], v[124:127]
	v_mfma_f32_16x16x32_f16 v[128:131], v[160:163], v[250:253], v[128:131]
	s_waitcnt lgkmcnt(0)
	s_mov_b32 s47, s48
	v_add_u32_e32 v169, s47, v164
	v_mfma_f32_16x16x32_f16 v[4:7], v[132:135], v[184:187], v[4:7]
	ds_read_b128 v[238:241], v169 offset:4112
	v_mfma_f32_16x16x32_f16 v[8:11], v[136:139], v[184:187], v[8:11]
	ds_read_b128 v[242:245], v169 offset:5136
	v_mfma_f32_16x16x32_f16 v[12:15], v[140:143], v[184:187], v[12:15]
	ds_read_b128 v[246:249], v169 offset:6160
	v_mfma_f32_16x16x32_f16 v[16:19], v[144:147], v[184:187], v[16:19]
	ds_read_b128 v[250:253], v169 offset:7184
	v_mfma_f32_16x16x32_f16 v[20:23], v[132:135], v[188:191], v[20:23]
	v_mfma_f32_16x16x32_f16 v[24:27], v[136:139], v[188:191], v[24:27]
	v_mfma_f32_16x16x32_f16 v[28:31], v[140:143], v[188:191], v[28:31]
	v_mfma_f32_16x16x32_f16 v[32:35], v[144:147], v[188:191], v[32:35]
	v_mfma_f32_16x16x32_f16 v[36:39], v[132:135], v[192:195], v[36:39]
	v_mfma_f32_16x16x32_f16 v[40:43], v[136:139], v[192:195], v[40:43]
	v_mfma_f32_16x16x32_f16 v[44:47], v[140:143], v[192:195], v[44:47]
	v_mfma_f32_16x16x32_f16 v[48:51], v[144:147], v[192:195], v[48:51]
	v_mfma_f32_16x16x32_f16 v[52:55], v[132:135], v[196:199], v[52:55]
	v_mfma_f32_16x16x32_f16 v[56:59], v[136:139], v[196:199], v[56:59]
	v_mfma_f32_16x16x32_f16 v[60:63], v[140:143], v[196:199], v[60:63]
	v_mfma_f32_16x16x32_f16 v[64:67], v[144:147], v[196:199], v[64:67]
	s_waitcnt vmcnt(0) lgkmcnt(0)
	s_barrier
	s_add_i32 s48, s47, 0x8000
	s_cmp_lg_u32 s47, 0x18000
	s_cselect_b32 s48, s48, 0
	v_add_u32_e32 v168, s48, v165
	v_add_u32_e32 v169, s48, v164
	v_mfma_f32_16x16x32_f16 v[68:71], v[132:135], v[238:241], v[68:71]
	ds_read_b128 v[148:151], v168 offset:16
	ds_read_b128 v[184:187], v169 offset:16
	v_mfma_f32_16x16x32_f16 v[72:75], v[136:139], v[238:241], v[72:75]
	ds_read_b128 v[152:155], v168 offset:1040
	ds_read_b128 v[188:191], v169 offset:1040
	v_mfma_f32_16x16x32_f16 v[76:79], v[140:143], v[238:241], v[76:79]
	ds_read_b128 v[156:159], v168 offset:2064
	ds_read_b128 v[192:195], v169 offset:2064
	v_mfma_f32_16x16x32_f16 v[80:83], v[144:147], v[238:241], v[80:83]
	ds_read_b128 v[160:163], v168 offset:3088
	ds_read_b128 v[196:199], v169 offset:3088
	v_mfma_f32_16x16x32_f16 v[84:87], v[132:135], v[242:245], v[84:87]
	v_mfma_f32_16x16x32_f16 v[88:91], v[136:139], v[242:245], v[88:91]
	v_mfma_f32_16x16x32_f16 v[92:95], v[140:143], v[242:245], v[92:95]
	v_mfma_f32_16x16x32_f16 v[96:99], v[144:147], v[242:245], v[96:99]
	v_mfma_f32_16x16x32_f16 v[100:103], v[132:135], v[246:249], v[100:103]
	v_mfma_f32_16x16x32_f16 v[104:107], v[136:139], v[246:249], v[104:107]
	v_mfma_f32_16x16x32_f16 v[108:111], v[140:143], v[246:249], v[108:111]
	v_mfma_f32_16x16x32_f16 v[112:115], v[144:147], v[246:249], v[112:115]
	v_mfma_f32_16x16x32_f16 v[116:119], v[132:135], v[250:253], v[116:119]
	v_mfma_f32_16x16x32_f16 v[120:123], v[136:139], v[250:253], v[120:123]
	v_mfma_f32_16x16x32_f16 v[124:127], v[140:143], v[250:253], v[124:127]
	v_mfma_f32_16x16x32_f16 v[128:131], v[144:147], v[250:253], v[128:131]
	s_waitcnt lgkmcnt(0)
	s_mov_b32 s47, s48
	v_add_u32_e32 v169, s47, v164
	v_mfma_f32_16x16x32_f16 v[4:7], v[148:151], v[184:187], v[4:7]
	ds_read_b128 v[238:241], v169 offset:4112
	v_mfma_f32_16x16x32_f16 v[8:11], v[152:155], v[184:187], v[8:11]
	ds_read_b128 v[242:245], v169 offset:5136
	v_mfma_f32_16x16x32_f16 v[12:15], v[156:159], v[184:187], v[12:15]
	ds_read_b128 v[246:249], v169 offset:6160
	v_mfma_f32_16x16x32_f16 v[16:19], v[160:163], v[184:187], v[16:19]
	ds_read_b128 v[250:253], v169 offset:7184
	v_mfma_f32_16x16x32_f16 v[20:23], v[148:151], v[188:191], v[20:23]
	v_mfma_f32_16x16x32_f16 v[24:27], v[152:155], v[188:191], v[24:27]
	v_mfma_f32_16x16x32_f16 v[28:31], v[156:159], v[188:191], v[28:31]
	v_mfma_f32_16x16x32_f16 v[32:35], v[160:163], v[188:191], v[32:35]
	v_mfma_f32_16x16x32_f16 v[36:39], v[148:151], v[192:195], v[36:39]
	v_mfma_f32_16x16x32_f16 v[40:43], v[152:155], v[192:195], v[40:43]
	v_mfma_f32_16x16x32_f16 v[44:47], v[156:159], v[192:195], v[44:47]
	v_mfma_f32_16x16x32_f16 v[48:51], v[160:163], v[192:195], v[48:51]
	v_mfma_f32_16x16x32_f16 v[52:55], v[148:151], v[196:199], v[52:55]
	v_mfma_f32_16x16x32_f16 v[56:59], v[152:155], v[196:199], v[56:59]
	v_mfma_f32_16x16x32_f16 v[60:63], v[156:159], v[196:199], v[60:63]
	v_mfma_f32_16x16x32_f16 v[64:67], v[160:163], v[196:199], v[64:67]
	s_waitcnt lgkmcnt(0)
	s_barrier
	v_mfma_f32_16x16x32_f16 v[68:71], v[148:151], v[238:241], v[68:71]
	v_mfma_f32_16x16x32_f16 v[72:75], v[152:155], v[238:241], v[72:75]
	v_mfma_f32_16x16x32_f16 v[76:79], v[156:159], v[238:241], v[76:79]
	v_mfma_f32_16x16x32_f16 v[80:83], v[160:163], v[238:241], v[80:83]
	v_mfma_f32_16x16x32_f16 v[84:87], v[148:151], v[242:245], v[84:87]
	v_mfma_f32_16x16x32_f16 v[88:91], v[152:155], v[242:245], v[88:91]
	v_mfma_f32_16x16x32_f16 v[92:95], v[156:159], v[242:245], v[92:95]
	v_mfma_f32_16x16x32_f16 v[96:99], v[160:163], v[242:245], v[96:99]
	v_mfma_f32_16x16x32_f16 v[100:103], v[148:151], v[246:249], v[100:103]
	v_mfma_f32_16x16x32_f16 v[104:107], v[152:155], v[246:249], v[104:107]
	v_mfma_f32_16x16x32_f16 v[108:111], v[156:159], v[246:249], v[108:111]
	v_mfma_f32_16x16x32_f16 v[112:115], v[160:163], v[246:249], v[112:115]
	v_mfma_f32_16x16x32_f16 v[116:119], v[148:151], v[250:253], v[116:119]
	v_mfma_f32_16x16x32_f16 v[120:123], v[152:155], v[250:253], v[120:123]
	v_mfma_f32_16x16x32_f16 v[124:127], v[156:159], v[250:253], v[124:127]
	v_mfma_f32_16x16x32_f16 v[128:131], v[160:163], v[250:253], v[128:131]
	s_mul_i32 s82, s52, 0xc00
	s_add_u32 s80, s28, s82
	s_addc_u32 s81, s29, 0
	s_lshl_b32 s82, s51, 1
	s_add_u32 s80, s80, s82
	s_addc_u32 s81, s81, 0
	v_and_b32_e32 v172, 15, v200
	v_bfe_u32 v173, v200, 4, 2
	v_bfe_u32 v174, v200, 6, 2
	v_bfe_u32 v175, v200, 8, 1
	v_lshl_or_b32 v175, v175, 7, v172
	v_mul_u32_u24_e32 v175, 0xc00, v175
	v_lshlrev_b32_e32 v174, 6, v174
	v_lshl_or_b32 v174, v173, 2, v174
	v_lshl_add_u32 v177, v174, 1, v175
	v_and_b32_e32 v172, 1, v173
	v_mul_u32_u24_e32 v172, 24, v172
	v_add_u32_e32 v177, v177, v172
	v_cvt_pk_f16_f32 v172, v4, v5
	v_cvt_pk_f16_f32 v173, v6, v7
	v_cvt_pk_f16_f32 v174, v8, v9
	v_cvt_pk_f16_f32 v175, v10, v11
	s_nop 1
	v_permlane16_swap_b32_e32 v172, v174
	v_permlane16_swap_b32_e32 v173, v175
	global_store_dwordx4 v177, v[172:175], s[80:81]
	v_cvt_pk_f16_f32 v228, v12, v13
	v_cvt_pk_f16_f32 v229, v14, v15
	v_cvt_pk_f16_f32 v230, v16, v17
	v_cvt_pk_f16_f32 v231, v18, v19
	s_nop 1
	v_permlane16_swap_b32_e32 v228, v230
	v_permlane16_swap_b32_e32 v229, v231
	global_store_dwordx4 v177, v[228:231], s[80:81] offset:64
	v_add_u32_e32 v177, 0xc000, v177
	v_cvt_pk_f16_f32 v172, v20, v21
	v_cvt_pk_f16_f32 v173, v22, v23
	v_cvt_pk_f16_f32 v174, v24, v25
	v_cvt_pk_f16_f32 v175, v26, v27
	s_nop 1
	v_permlane16_swap_b32_e32 v172, v174
	v_permlane16_swap_b32_e32 v173, v175
	global_store_dwordx4 v177, v[172:175], s[80:81]
	v_cvt_pk_f16_f32 v228, v28, v29
	v_cvt_pk_f16_f32 v229, v30, v31
	v_cvt_pk_f16_f32 v230, v32, v33
	v_cvt_pk_f16_f32 v231, v34, v35
	s_nop 1
	v_permlane16_swap_b32_e32 v228, v230
	v_permlane16_swap_b32_e32 v229, v231
	global_store_dwordx4 v177, v[228:231], s[80:81] offset:64
	v_add_u32_e32 v177, 0xc000, v177
	v_cvt_pk_f16_f32 v172, v36, v37
	v_cvt_pk_f16_f32 v173, v38, v39
	v_cvt_pk_f16_f32 v174, v40, v41
	v_cvt_pk_f16_f32 v175, v42, v43
	s_nop 1
	v_permlane16_swap_b32_e32 v172, v174
	v_permlane16_swap_b32_e32 v173, v175
	global_store_dwordx4 v177, v[172:175], s[80:81]
	v_cvt_pk_f16_f32 v228, v44, v45
	v_cvt_pk_f16_f32 v229, v46, v47
	v_cvt_pk_f16_f32 v230, v48, v49
	v_cvt_pk_f16_f32 v231, v50, v51
	s_nop 1
	v_permlane16_swap_b32_e32 v228, v230
	v_permlane16_swap_b32_e32 v229, v231
	global_store_dwordx4 v177, v[228:231], s[80:81] offset:64
	v_add_u32_e32 v177, 0xc000, v177
	v_cvt_pk_f16_f32 v172, v52, v53
	v_cvt_pk_f16_f32 v173, v54, v55
	v_cvt_pk_f16_f32 v174, v56, v57
	v_cvt_pk_f16_f32 v175, v58, v59
	s_nop 1
	v_permlane16_swap_b32_e32 v172, v174
	v_permlane16_swap_b32_e32 v173, v175
	global_store_dwordx4 v177, v[172:175], s[80:81]
	v_cvt_pk_f16_f32 v228, v60, v61
	v_cvt_pk_f16_f32 v229, v62, v63
	v_cvt_pk_f16_f32 v230, v64, v65
	v_cvt_pk_f16_f32 v231, v66, v67
	s_nop 1
	v_permlane16_swap_b32_e32 v228, v230
	v_permlane16_swap_b32_e32 v229, v231
	global_store_dwordx4 v177, v[228:231], s[80:81] offset:64
	v_add_u32_e32 v177, 0xc000, v177
	v_cvt_pk_f16_f32 v172, v68, v69
	v_cvt_pk_f16_f32 v173, v70, v71
	v_cvt_pk_f16_f32 v174, v72, v73
	v_cvt_pk_f16_f32 v175, v74, v75
	s_nop 1
	v_permlane16_swap_b32_e32 v172, v174
	v_permlane16_swap_b32_e32 v173, v175
	global_store_dwordx4 v177, v[172:175], s[80:81]
	v_cvt_pk_f16_f32 v228, v76, v77
	v_cvt_pk_f16_f32 v229, v78, v79
	v_cvt_pk_f16_f32 v230, v80, v81
	v_cvt_pk_f16_f32 v231, v82, v83
	s_nop 1
	v_permlane16_swap_b32_e32 v228, v230
	v_permlane16_swap_b32_e32 v229, v231
	global_store_dwordx4 v177, v[228:231], s[80:81] offset:64
	v_add_u32_e32 v177, 0xc000, v177
	v_cvt_pk_f16_f32 v172, v84, v85
	v_cvt_pk_f16_f32 v173, v86, v87
	v_cvt_pk_f16_f32 v174, v88, v89
	v_cvt_pk_f16_f32 v175, v90, v91
	s_nop 1
	v_permlane16_swap_b32_e32 v172, v174
	v_permlane16_swap_b32_e32 v173, v175
	global_store_dwordx4 v177, v[172:175], s[80:81]
	v_cvt_pk_f16_f32 v228, v92, v93
	v_cvt_pk_f16_f32 v229, v94, v95
	v_cvt_pk_f16_f32 v230, v96, v97
	v_cvt_pk_f16_f32 v231, v98, v99
	s_nop 1
	v_permlane16_swap_b32_e32 v228, v230
	v_permlane16_swap_b32_e32 v229, v231
	global_store_dwordx4 v177, v[228:231], s[80:81] offset:64
	v_add_u32_e32 v177, 0xc000, v177
	v_cvt_pk_f16_f32 v172, v100, v101
	v_cvt_pk_f16_f32 v173, v102, v103
	v_cvt_pk_f16_f32 v174, v104, v105
	v_cvt_pk_f16_f32 v175, v106, v107
	s_nop 1
	v_permlane16_swap_b32_e32 v172, v174
	v_permlane16_swap_b32_e32 v173, v175
	global_store_dwordx4 v177, v[172:175], s[80:81]
	v_cvt_pk_f16_f32 v228, v108, v109
	v_cvt_pk_f16_f32 v229, v110, v111
	v_cvt_pk_f16_f32 v230, v112, v113
	v_cvt_pk_f16_f32 v231, v114, v115
	s_nop 1
	v_permlane16_swap_b32_e32 v228, v230
	v_permlane16_swap_b32_e32 v229, v231
	global_store_dwordx4 v177, v[228:231], s[80:81] offset:64
	v_add_u32_e32 v177, 0xc000, v177
	v_cvt_pk_f16_f32 v172, v116, v117
	v_cvt_pk_f16_f32 v173, v118, v119
	v_cvt_pk_f16_f32 v174, v120, v121
	v_cvt_pk_f16_f32 v175, v122, v123
	s_nop 1
	v_permlane16_swap_b32_e32 v172, v174
	v_permlane16_swap_b32_e32 v173, v175
	global_store_dwordx4 v177, v[172:175], s[80:81]
	v_cvt_pk_f16_f32 v228, v124, v125
	v_cvt_pk_f16_f32 v229, v126, v127
	v_cvt_pk_f16_f32 v230, v128, v129
	v_cvt_pk_f16_f32 v231, v130, v131
	s_nop 1
	v_permlane16_swap_b32_e32 v228, v230
	v_permlane16_swap_b32_e32 v229, v231
	global_store_dwordx4 v177, v[228:231], s[80:81] offset:64
	s_nop 1
	s_add_i32 s46, s46, s76
	s_cmp_ge_i32 s46, s59
	s_cbranch_scc1 .LBB0_1133
	s_branch .LBB0_1121
